# all four GEMM main loops: one static s_setprio 1 for waves 4-7, per-segment flips replaced by s_nop, placement +4 mod 64
# speedup vs baseline: 1.0167x; 1.0039x over previous
; __device__ __forceinline__ unsigned xb_ld(unsigned* p)              { return __hip_atomic_load(p, __ATOMIC_RELAXED, __HIP_MEMORY_SCOPE_AGENT); }
; __device__ __forceinline__ unsigned xb_add(unsigned* p, unsigned v) { return __hip_atomic_fetch_add(p, v, __ATOMIC_RELAXED, __HIP_MEMORY_SCOPE_AGENT); }
; __device__ __forceinline__ void xcd_barrier_complete(unsigned* bar, unsigned x, unsigned& nloc, unsigned& nx) {
;     const unsigned G = gridDim.x * gridDim.y * gridDim.z;
;     unsigned sum, cnt, mine, sp = 0u;
;     for (;;) {
;         sum = 0u; cnt = 0u; mine = 0u;
; #pragma unroll
;         for (unsigned j = 0; j < 16; ++j) { const unsigned c = xb_ld(&bar[XB_XCNT(j)]); sum += c; cnt += (c > 0u) ? 1u : 0u; mine = (j == x) ? c : mine; }
;         if (sum == G) break;
;         __builtin_amdgcn_s_sleep(1);
;         if ((++sp & 255u) == 0u) { if (xb_ld(&bar[XB_TMO])) break; if (sp > XB_SPIN_CAP) { atomicAdd(&bar[XB_TMO], 1u); break; } }
;     }
;     nloc = mine > 0u ? mine : 1u; nx = cnt > 0u ? cnt : 1u;
; }
; __device__ __forceinline__ void xcd_barrier(const XcdBarrier& b) {
;     asm volatile("s_waitcnt vmcnt(0)" ::: "memory");
;     __syncthreads();
;     if (threadIdx.x == 0) {
;         unsigned* bar = b.bar;
;         __builtin_amdgcn_s_waitcnt(0);
;         unsigned nloc = b.st[0], nx = b.st[1];
;         if (nloc == 0u) { xcd_barrier_complete(bar, b.x, nloc, nx); b.st[0] = nloc; b.st[1] = nx; }
;         const unsigned old = xb_add(&bar[XB_XSUB(b.x)], 1u);
;         const unsigned gen = old / nloc;
;         if (old + 1u == (gen + 1u) * nloc) {
;             __builtin_amdgcn_fence(__ATOMIC_RELEASE, "agent");
;             asm volatile("s_waitcnt vmcnt(0)" ::: "memory");
;             const unsigned og = xb_add(&bar[XB_TOP], 1u);
;             const unsigned tg = og / nx;
;             if (og + 1u == (tg + 1u) * nx) xb_add(&bar[XB_TOPGEN], 1u);
;             else XB_SPIN(xb_ld(&bar[XB_TOPGEN]) == tg, bar);
;             __builtin_amdgcn_fence(__ATOMIC_ACQUIRE, "agent");
;             xb_add(&bar[XB_XGEN(b.x)], 1u);
;             asm volatile("s_waitcnt vmcnt(0)" ::: "memory");
;         } else {
;             XB_SPIN(xb_ld(&bar[XB_XGEN(b.x)]) == gen, bar);
; __global__ void __launch_bounds__(NTHREADS, 2) mega(Args a) {
;     ...
;     XcdBarrier xbar = xcd_barrier_post((unsigned*)(a.ws + WS_BAR), bst);
;     int ph = 0;
.LBB0_103:
	s_mul_i32 s2, s75, s74
	s_ashr_i32 s75, s74, 31
	s_cmp_gt_i32 s73, -1
	s_cselect_b64 s[4:5], -1, 0
	v_writelane_b32 v250, s4, 11
	s_mul_i32 s2, s2, s46
	v_lshrrev_b32_e32 v1, 20, v0
	v_writelane_b32 v250, s5, 12
	v_writelane_b32 v250, s2, 13
	s_add_u32 s2, s70, 0x5da0200
	s_addc_u32 s3, s71, 0
	v_writelane_b32 v250, s2, 14
	v_lshrrev_b32_e32 v0, 10, v0
	v_or_b32_e32 v0, v0, v1
	v_writelane_b32 v250, s3, 15
	s_add_u32 s2, s70, 0x5da0400
	s_addc_u32 s3, s71, 0
	v_writelane_b32 v250, s2, 16
	s_mov_b32 s39, 0
	v_mov_b32_e32 v223, 0x358637bd
	v_writelane_b32 v250, s3, 17
	s_add_u32 s2, s70, 0x5da0500
	s_addc_u32 s3, s71, 0
	v_writelane_b32 v250, s2, 18
	v_mov_b32_e32 v224, 0xc0135761
	v_mov_b32_e32 v225, 1
	v_writelane_b32 v250, s3, 19
	s_add_u32 s2, s70, 0x5da0600
	s_addc_u32 s3, s71, 0
	v_writelane_b32 v250, s2, 20
	v_mov_b32_e32 v226, 0x3ecc95a3
	v_mov_b32_e32 v227, 0x3c088889
	v_writelane_b32 v250, s3, 21
	s_add_u32 s2, s70, 0x5da0700
	s_addc_u32 s3, s71, 0
	v_writelane_b32 v250, s2, 22
	v_mov_b32_e32 v228, 0x260
	v_mov_b64_e32 v[186:187], 0x440
	v_writelane_b32 v250, s3, 23
	s_add_u32 s2, s70, 0x5da0800
	s_addc_u32 s3, s71, 0
	v_writelane_b32 v250, s2, 24
	v_mov_b64_e32 v[188:189], 0x43f
	v_mov_b32_e32 v190, 0x3f317218
	v_writelane_b32 v250, s3, 25
	s_add_u32 s2, s70, 0x5da0900
	s_addc_u32 s3, s71, 0
	v_writelane_b32 v250, s2, 26
	v_mov_b32_e32 v229, 0x7f800000
	v_mov_b32_e32 v230, 0x7fc00000
	v_writelane_b32 v250, s3, 27
	s_add_u32 s2, s70, 0x5da0a00
	s_addc_u32 s3, s71, 0
	v_writelane_b32 v250, s2, 28
	v_mov_b32_e32 v231, 0xff800000
	v_mov_b64_e32 v[192:193], 0x21f
	v_writelane_b32 v250, s3, 29
	s_add_u32 s2, s70, 0x5da0b00
	s_addc_u32 s3, s71, 0
	v_writelane_b32 v250, s2, 30
	v_mov_b64_e32 v[194:195], 0xbb0
	v_mov_b64_e32 v[196:197], 0xbaf
	v_writelane_b32 v250, s3, 31
	s_add_u32 s2, s70, 0x5da0c00
	s_addc_u32 s3, s71, 0
	v_writelane_b32 v250, s2, 32
	v_mov_b64_e32 v[198:199], 0x1ff
	s_movk_i32 s92, 0x2000
	v_writelane_b32 v250, s3, 33
	s_add_u32 s2, s70, 0x5da0d00
	s_addc_u32 s3, s71, 0
	v_writelane_b32 v250, s2, 34
	s_mov_b32 s29, 0x800000
	s_movk_i32 s30, 0x80
	v_writelane_b32 v250, s3, 35
	s_add_u32 s2, s70, 0x5da0e00
	s_addc_u32 s3, s71, 0
	v_writelane_b32 v250, s2, 36
	s_mov_b32 s31, 0xbe99999a
	s_movk_i32 s34, 0x2c00
	v_writelane_b32 v250, s3, 37
	s_add_u32 s2, s70, 0x5da0f00
	s_addc_u32 s3, s71, 0
	v_writelane_b32 v250, s2, 38
	s_mov_b32 s93, 0
	s_mov_b64 s[96:97], 0x2000
	v_writelane_b32 v250, s3, 39
	s_add_u32 s2, s70, 0x5da1000
	s_addc_u32 s3, s71, 0
	v_writelane_b32 v250, s2, 40
	s_mov_b64 s[84:85], 0x8000
	s_nop 0
	v_writelane_b32 v250, s3, 41
	s_add_u32 s2, s70, 0x5da1100
	s_addc_u32 s3, s71, 0
	v_writelane_b32 v250, s2, 42
	s_nop 1
	v_writelane_b32 v250, s3, 43
	s_add_u32 s2, s70, 0x5da1200
	s_addc_u32 s3, s71, 0
	v_writelane_b32 v250, s2, 44
	s_nop 1
	v_writelane_b32 v250, s3, 45
	s_add_u32 s2, s70, 0x5da1300
	s_addc_u32 s3, s71, 0
	v_writelane_b32 v250, s2, 46
	s_cmp_eq_u32 s33, 15
	s_nop 0
	v_writelane_b32 v250, s3, 47
	s_cselect_b64 s[2:3], -1, 0
	v_writelane_b32 v250, s2, 48
	s_cmp_eq_u32 s33, 14
	s_nop 0
	v_writelane_b32 v250, s3, 49
	s_cselect_b64 s[2:3], -1, 0
	v_writelane_b32 v250, s2, 50
	s_cmp_eq_u32 s33, 13
	s_nop 0
	v_writelane_b32 v250, s3, 51
	s_cselect_b64 s[2:3], -1, 0
	v_writelane_b32 v250, s2, 52
	s_cmp_eq_u32 s33, 12
	s_nop 0
	v_writelane_b32 v250, s3, 53
	s_cselect_b64 s[2:3], -1, 0
	v_writelane_b32 v250, s2, 54
	s_cmp_eq_u32 s33, 11
	s_nop 0
	v_writelane_b32 v250, s3, 55
	s_cselect_b64 s[2:3], -1, 0
	v_writelane_b32 v250, s2, 56
	s_cmp_eq_u32 s33, 10
	s_nop 0
	v_writelane_b32 v250, s3, 57
	s_cselect_b64 s[2:3], -1, 0
	v_writelane_b32 v250, s2, 58
	s_cmp_eq_u32 s33, 9
	s_nop 0
	v_writelane_b32 v250, s3, 59
	s_cselect_b64 s[2:3], -1, 0
	v_writelane_b32 v250, s2, 60
	s_cmp_eq_u32 s33, 8
	s_nop 0
	v_writelane_b32 v250, s3, 61
	s_cselect_b64 s[2:3], -1, 0
	v_writelane_b32 v250, s2, 62
	s_cmp_eq_u32 s33, 7
	s_nop 0
	v_writelane_b32 v250, s3, 63
	s_cselect_b64 s[2:3], -1, 0
	v_writelane_b32 v249, s2, 0
	s_cmp_eq_u32 s33, 6
	s_nop 0
	v_writelane_b32 v249, s3, 1
	s_cselect_b64 s[2:3], -1, 0
	v_writelane_b32 v249, s2, 2
	s_cmp_eq_u32 s33, 5
	s_nop 0
	v_writelane_b32 v249, s3, 3
	s_cselect_b64 s[2:3], -1, 0
	v_writelane_b32 v249, s2, 4
	s_cmp_eq_u32 s33, 4
	s_nop 0
	v_writelane_b32 v249, s3, 5
	s_cselect_b64 s[2:3], -1, 0
	v_writelane_b32 v249, s2, 6
	s_cmp_eq_u32 s33, 3
	s_nop 0
	v_writelane_b32 v249, s3, 7
	s_cselect_b64 s[2:3], -1, 0
	v_writelane_b32 v249, s2, 8
	s_cmp_eq_u32 s33, 2
	s_nop 0
	v_writelane_b32 v249, s3, 9
	s_cselect_b64 s[2:3], -1, 0
	v_writelane_b32 v249, s2, 10
	s_cmp_eq_u32 s33, 1
	s_nop 0
	v_writelane_b32 v249, s3, 11
	s_cselect_b64 s[2:3], -1, 0
	v_writelane_b32 v249, s2, 12
	s_cmp_eq_u32 s33, 0
	s_nop 0
	v_writelane_b32 v249, s3, 13
	s_cselect_b64 s[2:3], -1, 0
	v_writelane_b32 v249, s2, 14
	s_nop 1
	v_writelane_b32 v249, s3, 15
	s_lshl_b32 s2, s33, 8
	s_add_u32 s0, s0, s2
	s_addc_u32 s1, s1, 0
	s_add_u32 s2, s0, 0x1400
	s_addc_u32 s3, s1, 0
	v_writelane_b32 v249, s2, 16
	s_add_u32 s0, s0, 0x2400
	s_addc_u32 s1, s1, 0
	v_writelane_b32 v249, s3, 17
	v_writelane_b32 v249, s0, 18
	s_nop 1
	v_writelane_b32 v249, s1, 19
	s_movk_i32 s0, 0x3ff
	v_and_or_b32 v0, v0, s0, v220
	s_add_u32 s0, s70, 0x5da3400
	s_addc_u32 s1, s71, 0
	v_writelane_b32 v249, s0, 20
	s_nop 1
	v_writelane_b32 v249, s1, 21
	s_add_u32 s0, s70, 0x5da3500
	s_addc_u32 s1, s71, 0
	v_writelane_b32 v249, s0, 22
	s_lshl_b32 s66, s74, 9
	v_cvt_f32_u32_e32 v1, s66
	v_writelane_b32 v249, s1, 23
	s_load_dwordx4 s[0:3], s[60:61], 0x0
	s_mov_b32 s67, s66
	v_rcp_iflag_f32_e32 v1, v1
	s_waitcnt lgkmcnt(0)
; __device__ __forceinline__ unsigned xb_ld(unsigned* p)              { return __hip_atomic_load(p, __ATOMIC_RELAXED, __HIP_MEMORY_SCOPE_AGENT); }
; __device__ __forceinline__ unsigned xb_add(unsigned* p, unsigned v) { return __hip_atomic_fetch_add(p, v, __ATOMIC_RELAXED, __HIP_MEMORY_SCOPE_AGENT); }
; __device__ __forceinline__ void xcd_barrier_complete(unsigned* bar, unsigned x, unsigned& nloc, unsigned& nx) {
;     const unsigned G = gridDim.x * gridDim.y * gridDim.z;
;     unsigned sum, cnt, mine, sp = 0u;
;     for (;;) {
;         sum = 0u; cnt = 0u; mine = 0u;
; #pragma unroll
;         for (unsigned j = 0; j < 16; ++j) { const unsigned c = xb_ld(&bar[XB_XCNT(j)]); sum += c; cnt += (c > 0u) ? 1u : 0u; mine = (j == x) ? c : mine; }
;         if (sum == G) break;
;         __builtin_amdgcn_s_sleep(1);
;         if ((++sp & 255u) == 0u) { if (xb_ld(&bar[XB_TMO])) break; if (sp > XB_SPIN_CAP) { atomicAdd(&bar[XB_TMO], 1u); break; } }
;     }
;     nloc = mine > 0u ? mine : 1u; nx = cnt > 0u ? cnt : 1u;
; }
; __device__ __forceinline__ void xcd_barrier(const XcdBarrier& b) {
;     asm volatile("s_waitcnt vmcnt(0)" ::: "memory");
;     __syncthreads();
;     if (threadIdx.x == 0) {
;         unsigned* bar = b.bar;
;         __builtin_amdgcn_s_waitcnt(0);
;         unsigned nloc = b.st[0], nx = b.st[1];
;         if (nloc == 0u) { xcd_barrier_complete(bar, b.x, nloc, nx); b.st[0] = nloc; b.st[1] = nx; }
;         const unsigned old = xb_add(&bar[XB_XSUB(b.x)], 1u);
;         const unsigned gen = old / nloc;
;         if (old + 1u == (gen + 1u) * nloc) {
;             __builtin_amdgcn_fence(__ATOMIC_RELEASE, "agent");
;             asm volatile("s_waitcnt vmcnt(0)" ::: "memory");
;             const unsigned og = xb_add(&bar[XB_TOP], 1u);
;             const unsigned tg = og / nx;
;             if (og + 1u == (tg + 1u) * nx) xb_add(&bar[XB_TOPGEN], 1u);
;             else XB_SPIN(xb_ld(&bar[XB_TOPGEN]) == tg, bar);
;             __builtin_amdgcn_fence(__ATOMIC_ACQUIRE, "agent");
;             xb_add(&bar[XB_XGEN(b.x)], 1u);
;             asm volatile("s_waitcnt vmcnt(0)" ::: "memory");
;         } else {
;             XB_SPIN(xb_ld(&bar[XB_XGEN(b.x)]) == gen, bar);
; __global__ void __launch_bounds__(NTHREADS, 2) mega(Args a) {
;     ...
;     XcdBarrier xbar = xcd_barrier_post((unsigned*)(a.ws + WS_BAR), bst);
;     int ph = 0;
	s_add_u32 s0, s2, 0xf8000000
	v_writelane_b32 v249, s0, 24
	s_addc_u32 s0, s3, -1
	v_writelane_b32 v249, s0, 25
	s_add_i32 s0, s74, 0x21f
	v_writelane_b32 v249, s0, 26
	s_lshl_b32 s0, s74, 1
	v_writelane_b32 v249, s0, 27
	s_add_i32 s0, s74, 0x1ff
	v_writelane_b32 v249, s0, 28
	s_and_b32 s0, s74, 7
	s_lshl_b32 s70, s74, 3
	v_mul_f32_e32 v1, 0x4f7ffffe, v1
	s_cmp_lg_u32 s0, 0
	v_cvt_u32_f32_e32 v1, v1
	s_cselect_b64 s[0:1], -1, 0
	v_writelane_b32 v249, s0, 29
	s_lshl_b32 s26, s74, 10
	s_ashr_i32 s71, s70, 31
	v_writelane_b32 v249, s1, 30
	s_sub_i32 s0, 0, s66
	v_mul_lo_u32 v2, s0, v1
	s_abs_i32 s0, s74
	v_cvt_f32_u32_e32 v3, s0
	v_writelane_b32 v249, s0, 31
	s_sub_i32 s0, 0, s0
	v_mul_hi_u32 v2, v1, v2
	v_rcp_iflag_f32_e32 v3, v3
	v_add_u32_e32 v222, v1, v2
	s_lshl_b64 s[90:91], s[70:71], 13
	v_mbcnt_lo_u32_b32 v2, -1, 0
	v_mul_f32_e32 v3, 0x4f7ffffe, v3
	v_cvt_u32_f32_e32 v3, v3
	v_mov_b32_e32 v1, 0
	v_mbcnt_hi_u32_b32 v221, -1, v2
	v_readfirstlane_b32 s1, v3
	s_mul_i32 s0, s0, s1
	s_mul_hi_u32 s0, s1, s0
	s_add_i32 s0, s1, s0
	v_writelane_b32 v249, s0, 32
	s_mov_b32 s1, -1
	s_mov_b32 s0, s39
	s_and_b64 s[0:1], s[66:67], s[0:1]
	v_writelane_b32 v249, s0, 33
	s_ashr_i32 s67, s66, 31
	s_lshl_b64 s[56:57], s[66:67], 2
	v_writelane_b32 v249, s1, 34
	s_mov_b32 s0, 1
	v_writelane_b32 v249, s0, 35
	v_writelane_b32 v249, s26, 36
	s_lshl_b32 s0, s74, 7
	v_writelane_b32 v249, s0, 37
	s_lshl_b32 s0, s74, 8
	v_writelane_b32 v249, s0, 38
	s_add_i32 s0, 0, 0x20000
	v_writelane_b32 v249, s0, 39
	s_add_i32 s0, 0, 0x20004
	v_writelane_b32 v249, s0, 40
	v_cmp_eq_u32_e64 s[0:1], 0, v0
	s_mov_b64 s[94:95], s[56:57]
	s_nop 0
	v_writelane_b32 v249, s0, 41
	s_nop 1
	v_writelane_b32 v249, s1, 42
	s_lshl_b64 s[0:1], s[70:71], 2
	v_writelane_b32 v249, s0, 43
	s_nop 1
	v_writelane_b32 v249, s1, 44
	s_lshl_b64 s[0:1], s[70:71], 12
	v_writelane_b32 v249, s0, 45
	v_readlane_b32 s71, v250, 0
	s_nop 0
	v_writelane_b32 v249, s1, 46
	s_mov_b64 s[0:1], -1
	v_writelane_b32 v249, s0, 47
	s_nop 1
	v_writelane_b32 v249, s1, 48
	s_mov_b64 s[0:1], 0x80
	v_writelane_b32 v249, s90, 49
	s_nop 1
	v_writelane_b32 v249, s91, 50
	s_branch .LBB0_106
	s_nop 0
	s_nop 0
	s_nop 0
	s_nop 0
	s_nop 0
	s_nop 0
	s_nop 0
	s_nop 0
	s_nop 0
	s_nop 0
	s_nop 0
	s_nop 0
	s_nop 0
	s_nop 0

; #define PG8_STAGE(bufoff, gbase, voff) do { _Pragma("unroll") for (int _i = 0; _i < 2; ++_i) \
;         __builtin_amdgcn_global_load_lds((const unsigned*)((const char*)(gbase) + (voff)[_i]), (PG8_LAS unsigned*)(lds + (bufoff) + ldsw + _i * 8192), 16, 0, 0); } while (0)
; #define PG8_LDA(dst, b, h) do { _Pragma("unroll") for (int m = 0; m < 4; ++m) _Pragma("unroll") for (int k = 0; k < 2; ++k) dst[m][k] = *(const PG8_LAS bf16x8*)(lds + PG8_SA(b, h) + aoff + m * 2048 + k * 1024); } while (0)
; #define PG8_LDB(dst, b, h) do { _Pragma("unroll") for (int n = 0; n < 2; ++n) _Pragma("unroll") for (int k = 0; k < 2; ++k) dst[n][k] = *(const PG8_LAS bf16x8*)(lds + PG8_SB(b, h) + boff + n * 2048 + k * 1024); } while (0)
; #define PG8_WAIT_V(n) asm volatile("s_waitcnt vmcnt(" #n ")" ::: "memory")
; template <class Epi, class Sched, bool ALIGN_EPI = false, bool SP2 = false>
; __device__ __forceinline__ void gemm_phase(PG8_LAS unsigned char* lds, const Gemm g, const Sched& S, const Epi& E) {
;     ...
;         const bool has_next = S.next(ui + 1, nxt);
;         const char* nA = has_next ? (const char*)g.A + (size_t)nxt.pm * tstep + (size_t)nxt.kt0 * kstep : cA; const char* nB = has_next ? (const char*)g.Bt + (size_t)nxt.pn * tstep + (size_t)nxt.kt0 * kstep : cB;
;         const int nt = cur.nkt;
;         for (int t = 0; t < nt; t += 2) {
;             const bool last = (t == nt - 2);
;             const char* a1 = cA + (size_t)(t + 1) * kstep;
;             const char* a2 = last ? nA : cA + (size_t)(t + 2) * kstep; const char* b2 = last ? nB : cB + (size_t)(t + 2) * kstep;
;             const char* a3 = a2 + kstep; const char* b3 = b2 + kstep;
;             if (last && has_next) S.a_ready(nxt);
;             if constexpr (SP2) {
;             PG8_LDB(B0, 0, 0); PG8_LDB(B1, 0, 1); PG8_SCHED; PG8_LDA(At, 0, 0); PG8_STAGE(PG8_SA(1, 1), a1 + hstep, voffA);
;             PG8_WAIT_V(8); PG8_WAIT_L(0); PG8_BAR; PG8_MMA(0, 0, At, B0); PG8_MMA(0, 1, At, B1); PG8_BAR; PG8_SCHED;
;     ...
;         if (cur.ks != -2) {
; #pragma unroll
;         for (int a = 0; a < 2; ++a)
; #pragma unroll
;             for (int b = 0; b < 2; ++b)
; #pragma unroll
;                 for (int m = 0; m < 4; ++m)
; #pragma unroll
;                     for (int n = 0; n < 2; ++n) acc[a][b][m][n] = (f32x4){0.f, 0.f, 0.f, 0.f};
;         }
;         cur = nxt; cA = nA; cB = nB; ++ui;
.LBB0_117:
	s_ashr_i32 s21, s20, 31
	s_lshl_b64 s[2:3], s[20:21], 20
	s_add_u32 s44, s6, s2
	s_addc_u32 s45, s7, s3
	s_and_b64 s[2:3], s[40:41], exec
	s_cselect_b32 s21, s45, s51
	s_cselect_b32 s24, s44, s50
	s_ashr_i32 s19, s18, 31
	s_lshl_b64 s[2:3], s[18:19], 20
	s_add_u32 s46, s10, s2
	s_addc_u32 s47, s11, s3
	s_and_b64 s[2:3], s[40:41], exec
	s_cselect_b32 s19, s47, s23
	s_cselect_b32 s25, s46, s22
	s_add_u32 s43, s22, 0x100
	s_addc_u32 s56, s23, 0
	s_add_u32 s50, s50, 0x80080
	v_mov_b32_e32 v2, 0
	s_addc_u32 s51, s51, 0
	s_mov_b32 s57, -2
	v_mov_b32_e32 v3, v2
	v_mov_b32_e32 v4, v2
	v_mov_b32_e32 v5, v2
	v_mov_b32_e32 v6, v2
	v_mov_b32_e32 v7, v2
	v_mov_b32_e32 v8, v2
	v_mov_b32_e32 v9, v2
	v_mov_b32_e32 v18, v2
	v_mov_b32_e32 v19, v2
	v_mov_b32_e32 v20, v2
	v_mov_b32_e32 v21, v2
	v_mov_b32_e32 v22, v2
	v_mov_b32_e32 v23, v2
	v_mov_b32_e32 v24, v2
	v_mov_b32_e32 v25, v2
	s_waitcnt vmcnt(0)
	v_mov_b32_e32 v34, v2
	v_mov_b32_e32 v35, v2
	v_mov_b32_e32 v36, v2
	v_mov_b32_e32 v37, v2
	v_mov_b32_e32 v38, v2
	v_mov_b32_e32 v39, v2
	v_mov_b32_e32 v40, v2
	v_mov_b32_e32 v41, v2
	v_mov_b32_e32 v50, v2
	v_mov_b32_e32 v51, v2
	v_mov_b32_e32 v52, v2
	v_mov_b32_e32 v53, v2
	v_mov_b32_e32 v54, v2
	v_mov_b32_e32 v55, v2
	v_mov_b32_e32 v56, v2
	v_mov_b32_e32 v57, v2
	v_mov_b32_e32 v10, v2
	v_mov_b32_e32 v11, v2
	v_mov_b32_e32 v12, v2
	v_mov_b32_e32 v13, v2
	v_mov_b32_e32 v14, v2
	v_mov_b32_e32 v15, v2
	v_mov_b32_e32 v16, v2
	v_mov_b32_e32 v17, v2
	v_mov_b32_e32 v26, v2
	v_mov_b32_e32 v27, v2
	v_mov_b32_e32 v28, v2
	v_mov_b32_e32 v29, v2
	v_mov_b32_e32 v30, v2
	v_mov_b32_e32 v31, v2
	v_mov_b32_e32 v32, v2
	v_mov_b32_e32 v33, v2
	v_mov_b32_e32 v42, v2
	v_mov_b32_e32 v43, v2
	v_mov_b32_e32 v44, v2
	v_mov_b32_e32 v45, v2
	v_mov_b32_e32 v46, v2
	v_mov_b32_e32 v47, v2
	v_mov_b32_e32 v48, v2
	v_mov_b32_e32 v49, v2
	v_mov_b32_e32 v58, v2
	v_mov_b32_e32 v59, v2
	v_mov_b32_e32 v60, v2
	v_mov_b32_e32 v61, v2
	v_mov_b32_e32 v62, v2
	v_mov_b32_e32 v63, v2
	v_mov_b32_e32 v64, v2
	v_mov_b32_e32 v65, v2
	v_mov_b32_e32 v66, v2
	v_mov_b32_e32 v67, v2
	v_mov_b32_e32 v68, v2
	v_mov_b32_e32 v69, v2
	v_mov_b32_e32 v70, v2
	v_mov_b32_e32 v71, v2
	v_mov_b32_e32 v72, v2
	v_mov_b32_e32 v73, v2
	v_mov_b32_e32 v82, v2
	v_mov_b32_e32 v83, v2
	v_mov_b32_e32 v84, v2
	v_mov_b32_e32 v85, v2
	v_mov_b32_e32 v86, v2
	v_mov_b32_e32 v87, v2
	v_mov_b32_e32 v88, v2
	v_mov_b32_e32 v89, v2
	v_mov_b32_e32 v98, v2
	v_mov_b32_e32 v99, v2
	v_mov_b32_e32 v100, v2
	v_mov_b32_e32 v101, v2
	v_mov_b32_e32 v102, v2
	v_mov_b32_e32 v103, v2
	v_mov_b32_e32 v104, v2
	v_mov_b32_e32 v105, v2
	v_mov_b32_e32 v114, v2
	v_mov_b32_e32 v115, v2
	v_mov_b32_e32 v116, v2
	v_mov_b32_e32 v117, v2
	v_mov_b32_e32 v118, v2
	v_mov_b32_e32 v119, v2
	v_mov_b32_e32 v120, v2
	v_mov_b32_e32 v121, v2
	v_mov_b32_e32 v74, v2
	v_mov_b32_e32 v75, v2
	v_mov_b32_e32 v76, v2
	v_mov_b32_e32 v77, v2
	v_mov_b32_e32 v78, v2
	v_mov_b32_e32 v79, v2
	v_mov_b32_e32 v80, v2
	v_mov_b32_e32 v81, v2
	v_mov_b32_e32 v90, v2
	v_mov_b32_e32 v91, v2
	v_mov_b32_e32 v92, v2
	v_mov_b32_e32 v93, v2
	v_mov_b32_e32 v94, v2
	v_mov_b32_e32 v95, v2
	v_mov_b32_e32 v96, v2
	v_mov_b32_e32 v97, v2
	v_mov_b32_e32 v106, v2
	v_mov_b32_e32 v107, v2
	v_mov_b32_e32 v108, v2
	v_mov_b32_e32 v109, v2
	v_mov_b32_e32 v110, v2
	v_mov_b32_e32 v111, v2
	v_mov_b32_e32 v112, v2
	v_mov_b32_e32 v113, v2
	v_mov_b32_e32 v122, v2
	v_mov_b32_e32 v123, v2
	v_mov_b32_e32 v124, v2
	v_mov_b32_e32 v125, v2
	v_mov_b32_e32 v126, v2
	v_mov_b32_e32 v127, v2
	v_mov_b32_e32 v128, v2
	v_mov_b32_e32 v129, v2
	s_cmp_eq_u32 s16, 0
	s_cbranch_scc0 .Lmy_p1_prio_done
	s_setprio 1
.Lmy_p1_prio_done:
.LBB0_118:
	s_add_u32 s2, s50, 0xfff80080
	s_addc_u32 s3, s51, -1
	s_add_i32 s58, 0, 0x10000
	s_cmp_eq_u32 s57, 28
	s_cselect_b32 s53, s21, s3
	s_cselect_b32 s52, s24, s2
	s_cselect_b32 s23, s19, s56
	s_cselect_b32 s22, s25, s43
	s_add_i32 s59, 0, 0x14000
	v_add_u32_e32 v156, s58, v149
	v_add_u32_e32 v172, s59, v149
	ds_read_b128 v[140:143], v156
	ds_read_b128 v[144:147], v156 offset:1024
	ds_read_b128 v[152:155], v156 offset:2048
	ds_read_b128 v[156:159], v156 offset:3072
	ds_read_b128 v[160:163], v172
	ds_read_b128 v[164:167], v172 offset:1024
	ds_read_b128 v[168:171], v172 offset:2048
	ds_read_b128 v[172:175], v172 offset:3072
	v_lshl_add_u64 v[184:185], s[50:51], 0, v[138:139]
	s_add_i32 m0, s35, 0xc000
	ds_read_b128 v[176:179], v151
	ds_read_b128 v[180:183], v151 offset:1024
	ds_read_b128 v[200:203], v151 offset:2048
	ds_read_b128 v[204:207], v151 offset:3072
	ds_read_b128 v[208:211], v151 offset:4096
	ds_read_b128 v[212:215], v151 offset:5120
	ds_read_b128 v[216:219], v151 offset:6144
	ds_read_b128 v[232:235], v151 offset:7168
	global_load_lds_dwordx4 v[184:185], off
	v_lshl_add_u64 v[184:185], s[50:51], 0, v[136:137]
	s_add_i32 m0, s35, 0xe000
	s_nop 0
	global_load_lds_dwordx4 v[184:185], off
	s_waitcnt vmcnt(8)
	s_waitcnt lgkmcnt(0)
	s_barrier
; #define PG8_STAGE(bufoff, gbase, voff) do { _Pragma("unroll") for (int _i = 0; _i < 2; ++_i) \
;         __builtin_amdgcn_global_load_lds((const unsigned*)((const char*)(gbase) + (voff)[_i]), (PG8_LAS unsigned*)(lds + (bufoff) + ldsw + _i * 8192), 16, 0, 0); } while (0)
; #define PG8_LDA(dst, b, h) do { _Pragma("unroll") for (int m = 0; m < 4; ++m) _Pragma("unroll") for (int k = 0; k < 2; ++k) dst[m][k] = *(const PG8_LAS bf16x8*)(lds + PG8_SA(b, h) + aoff + m * 2048 + k * 1024); } while (0)
; #define PG8_MMA(ai, bj, At, Bt) do { __builtin_amdgcn_s_setprio(1); _Pragma("unroll") for (int m = 0; m < 4; ++m) _Pragma("unroll") for (int n = 0; n < 2; ++n) _Pragma("unroll") for (int k = 0; k < 2; ++k) \
;         acc[ai][bj][m][n] = __builtin_amdgcn_mfma_f32_16x16x32_bf16(Bt[n][k], At[m][k], acc[ai][bj][m][n], 0, 0, 0); __builtin_amdgcn_s_setprio(0); } while (0)
; #define PG8_WAIT_V(n) asm volatile("s_waitcnt vmcnt(" #n ")" ::: "memory")
; #define PG8_WAIT_L(n) asm volatile("s_waitcnt lgkmcnt(" #n ")" ::: "memory")
; #define PG8_BAR __builtin_amdgcn_s_barrier()
; #define PG8_SCHED __builtin_amdgcn_sched_barrier(0)
; template <class Epi, class Sched, bool ALIGN_EPI = false, bool SP2 = false>
; __device__ __forceinline__ void gemm_phase(PG8_LAS unsigned char* lds, const Gemm g, const Sched& S, const Epi& E) {
;     ...
;             PG8_WAIT_V(8); PG8_WAIT_L(0); PG8_BAR; PG8_MMA(0, 0, At, B0); PG8_MMA(0, 1, At, B1); PG8_BAR; PG8_SCHED;
;             PG8_LDA(At, 0, 1); PG8_STAGE(PG8_SB(0, 0), b2, voffB); PG8_STAGE(PG8_SB(0, 1), b2 + hstep, voffB); PG8_STAGE(PG8_SA(0, 0), a2, voffA);
;             PG8_WAIT_V(8); PG8_WAIT_L(0); PG8_BAR; PG8_MMA(1, 0, At, B0); PG8_MMA(1, 1, At, B1); PG8_BAR; PG8_SCHED;
	s_nop 0
	s_waitcnt lgkmcnt(0)
	v_mfma_f32_16x16x32_bf16 v[126:129], v[140:143], v[176:179], v[126:129]
	v_mfma_f32_16x16x32_bf16 v[122:125], v[152:155], v[176:179], v[122:125]
	v_mfma_f32_16x16x32_bf16 v[110:113], v[140:143], v[200:203], v[110:113]
	v_mfma_f32_16x16x32_bf16 v[106:109], v[152:155], v[200:203], v[106:109]
	v_mfma_f32_16x16x32_bf16 v[94:97], v[140:143], v[208:211], v[94:97]
	v_mfma_f32_16x16x32_bf16 v[90:93], v[152:155], v[208:211], v[90:93]
	v_mfma_f32_16x16x32_bf16 v[78:81], v[140:143], v[216:219], v[78:81]
	v_mfma_f32_16x16x32_bf16 v[74:77], v[152:155], v[216:219], v[74:77]
	v_mfma_f32_16x16x32_bf16 v[126:129], v[144:147], v[180:183], v[126:129]
	v_mfma_f32_16x16x32_bf16 v[122:125], v[156:159], v[180:183], v[122:125]
	v_mfma_f32_16x16x32_bf16 v[110:113], v[144:147], v[204:207], v[110:113]
	v_mfma_f32_16x16x32_bf16 v[106:109], v[156:159], v[204:207], v[106:109]
	v_mfma_f32_16x16x32_bf16 v[94:97], v[144:147], v[212:215], v[94:97]
	v_mfma_f32_16x16x32_bf16 v[90:93], v[156:159], v[212:215], v[90:93]
	v_mfma_f32_16x16x32_bf16 v[78:81], v[144:147], v[232:235], v[78:81]
	v_mfma_f32_16x16x32_bf16 v[74:77], v[156:159], v[232:235], v[74:77]
	s_nop 0
	s_nop 0
	v_mfma_f32_16x16x32_bf16 v[118:121], v[160:163], v[176:179], v[118:121]
	v_mfma_f32_16x16x32_bf16 v[114:117], v[168:171], v[176:179], v[114:117]
	v_mfma_f32_16x16x32_bf16 v[102:105], v[160:163], v[200:203], v[102:105]
	v_mfma_f32_16x16x32_bf16 v[98:101], v[168:171], v[200:203], v[98:101]
	v_mfma_f32_16x16x32_bf16 v[86:89], v[160:163], v[208:211], v[86:89]
	v_mfma_f32_16x16x32_bf16 v[82:85], v[168:171], v[208:211], v[82:85]
	v_mfma_f32_16x16x32_bf16 v[70:73], v[160:163], v[216:219], v[70:73]
	v_mfma_f32_16x16x32_bf16 v[66:69], v[168:171], v[216:219], v[66:69]
	v_mfma_f32_16x16x32_bf16 v[118:121], v[164:167], v[180:183], v[118:121]
	v_mfma_f32_16x16x32_bf16 v[114:117], v[172:175], v[180:183], v[114:117]
	v_mfma_f32_16x16x32_bf16 v[102:105], v[164:167], v[204:207], v[102:105]
	v_mfma_f32_16x16x32_bf16 v[98:101], v[172:175], v[204:207], v[98:101]
	v_mfma_f32_16x16x32_bf16 v[86:89], v[164:167], v[212:215], v[86:89]
	v_mfma_f32_16x16x32_bf16 v[82:85], v[172:175], v[212:215], v[82:85]
	v_mfma_f32_16x16x32_bf16 v[70:73], v[164:167], v[232:235], v[70:73]
	v_mfma_f32_16x16x32_bf16 v[66:69], v[172:175], v[232:235], v[66:69]
	s_nop 0
	s_barrier
	s_add_i32 s2, s58, s33
	v_lshl_add_u64 v[184:185], s[22:23], 0, v[0:1]
	s_mov_b32 m0, s2
	ds_read_b128 v[176:179], v151 offset:16384
	ds_read_b128 v[180:183], v151 offset:17408
	ds_read_b128 v[200:203], v151 offset:18432
	ds_read_b128 v[204:207], v151 offset:19456
	ds_read_b128 v[208:211], v151 offset:20480
	ds_read_b128 v[212:215], v151 offset:21504
	ds_read_b128 v[216:219], v151 offset:22528
	ds_read_b128 v[232:235], v151 offset:23552
	global_load_lds_dwordx4 v[184:185], off
	s_add_i32 m0, s2, 0x2000
	s_add_u32 s2, s22, 0x80000
	v_lshl_add_u64 v[236:237], s[22:23], 0, v[134:135]
	s_addc_u32 s3, s23, 0
	s_add_i32 s58, s59, s33
	global_load_lds_dwordx4 v[236:237], off
	v_lshl_add_u64 v[238:239], s[2:3], 0, v[0:1]
	s_mov_b32 m0, s58
	v_lshl_add_u64 v[240:241], s[52:53], 0, v[132:133]
	global_load_lds_dwordx4 v[238:239], off
	v_lshl_add_u64 v[238:239], s[2:3], 0, v[134:135]
	s_add_i32 m0, s58, 0x2000
	s_nop 0
	global_load_lds_dwordx4 v[238:239], off
	v_lshl_add_u64 v[238:239], s[52:53], 0, v[130:131]
	s_mov_b32 m0, s35
	s_nop 0
	global_load_lds_dwordx4 v[238:239], off
	s_mov_b32 m0, s36
	s_nop 0
	global_load_lds_dwordx4 v[240:241], off
	s_waitcnt vmcnt(8)
	s_waitcnt lgkmcnt(0)
	s_barrier
	s_nop 0
	s_waitcnt lgkmcnt(0)
	v_mfma_f32_16x16x32_bf16 v[62:65], v[140:143], v[176:179], v[62:65]
	v_mfma_f32_16x16x32_bf16 v[58:61], v[152:155], v[176:179], v[58:61]
	v_mfma_f32_16x16x32_bf16 v[46:49], v[140:143], v[200:203], v[46:49]
	v_mfma_f32_16x16x32_bf16 v[42:45], v[152:155], v[200:203], v[42:45]
	v_mfma_f32_16x16x32_bf16 v[30:33], v[140:143], v[208:211], v[30:33]
	v_mfma_f32_16x16x32_bf16 v[26:29], v[152:155], v[208:211], v[26:29]
	v_mfma_f32_16x16x32_bf16 v[14:17], v[140:143], v[216:219], v[14:17]
	v_mfma_f32_16x16x32_bf16 v[10:13], v[152:155], v[216:219], v[10:13]
	v_mfma_f32_16x16x32_bf16 v[62:65], v[144:147], v[180:183], v[62:65]
	v_mfma_f32_16x16x32_bf16 v[58:61], v[156:159], v[180:183], v[58:61]
	v_mfma_f32_16x16x32_bf16 v[46:49], v[144:147], v[204:207], v[46:49]
	v_mfma_f32_16x16x32_bf16 v[42:45], v[156:159], v[204:207], v[42:45]
	v_mfma_f32_16x16x32_bf16 v[30:33], v[144:147], v[212:215], v[30:33]
	v_mfma_f32_16x16x32_bf16 v[26:29], v[156:159], v[212:215], v[26:29]
	v_mfma_f32_16x16x32_bf16 v[14:17], v[144:147], v[232:235], v[14:17]
	v_mfma_f32_16x16x32_bf16 v[10:13], v[156:159], v[232:235], v[10:13]
	s_nop 0
	s_nop 0
	v_mfma_f32_16x16x32_bf16 v[54:57], v[160:163], v[176:179], v[54:57]
	v_mfma_f32_16x16x32_bf16 v[50:53], v[168:171], v[176:179], v[50:53]
	v_mfma_f32_16x16x32_bf16 v[38:41], v[160:163], v[200:203], v[38:41]
	v_mfma_f32_16x16x32_bf16 v[34:37], v[168:171], v[200:203], v[34:37]
	v_mfma_f32_16x16x32_bf16 v[22:25], v[160:163], v[208:211], v[22:25]
	v_mfma_f32_16x16x32_bf16 v[18:21], v[168:171], v[208:211], v[18:21]
	v_mfma_f32_16x16x32_bf16 v[6:9], v[160:163], v[216:219], v[6:9]
	v_mfma_f32_16x16x32_bf16 v[2:5], v[168:171], v[216:219], v[2:5]
	v_mfma_f32_16x16x32_bf16 v[54:57], v[164:167], v[180:183], v[54:57]
	v_mfma_f32_16x16x32_bf16 v[50:53], v[172:175], v[180:183], v[50:53]
	v_mfma_f32_16x16x32_bf16 v[38:41], v[164:167], v[204:207], v[38:41]
	v_mfma_f32_16x16x32_bf16 v[34:37], v[172:175], v[204:207], v[34:37]
	v_mfma_f32_16x16x32_bf16 v[22:25], v[164:167], v[212:215], v[22:25]
	v_mfma_f32_16x16x32_bf16 v[18:21], v[172:175], v[212:215], v[18:21]
	v_mfma_f32_16x16x32_bf16 v[6:9], v[164:167], v[232:235], v[6:9]
	v_mfma_f32_16x16x32_bf16 v[2:5], v[172:175], v[232:235], v[2:5]
	s_nop 0
	s_barrier
; #define PG8_STAGE(bufoff, gbase, voff) do { _Pragma("unroll") for (int _i = 0; _i < 2; ++_i) \
;         __builtin_amdgcn_global_load_lds((const unsigned*)((const char*)(gbase) + (voff)[_i]), (PG8_LAS unsigned*)(lds + (bufoff) + ldsw + _i * 8192), 16, 0, 0); } while (0)
; #define PG8_LDA(dst, b, h) do { _Pragma("unroll") for (int m = 0; m < 4; ++m) _Pragma("unroll") for (int k = 0; k < 2; ++k) dst[m][k] = *(const PG8_LAS bf16x8*)(lds + PG8_SA(b, h) + aoff + m * 2048 + k * 1024); } while (0)
; #define PG8_LDB(dst, b, h) do { _Pragma("unroll") for (int n = 0; n < 2; ++n) _Pragma("unroll") for (int k = 0; k < 2; ++k) dst[n][k] = *(const PG8_LAS bf16x8*)(lds + PG8_SB(b, h) + boff + n * 2048 + k * 1024); } while (0)
; #define PG8_MMA(ai, bj, At, Bt) do { __builtin_amdgcn_s_setprio(1); _Pragma("unroll") for (int m = 0; m < 4; ++m) _Pragma("unroll") for (int n = 0; n < 2; ++n) _Pragma("unroll") for (int k = 0; k < 2; ++k) \
;         acc[ai][bj][m][n] = __builtin_amdgcn_mfma_f32_16x16x32_bf16(Bt[n][k], At[m][k], acc[ai][bj][m][n], 0, 0, 0); __builtin_amdgcn_s_setprio(0); } while (0)
; #define PG8_WAIT_V(n) asm volatile("s_waitcnt vmcnt(" #n ")" ::: "memory")
; #define PG8_WAIT_L(n) asm volatile("s_waitcnt lgkmcnt(" #n ")" ::: "memory")
; #define PG8_BAR __builtin_amdgcn_s_barrier()
; #define PG8_SCHED __builtin_amdgcn_sched_barrier(0)
; template <class Epi, class Sched, bool ALIGN_EPI = false, bool SP2 = false>
; __device__ __forceinline__ void gemm_phase(PG8_LAS unsigned char* lds, const Gemm g, const Sched& S, const Epi& E) {
;     ...
;             PG8_LDB(B0, 1, 0); PG8_LDB(B1, 1, 1); PG8_SCHED; PG8_LDA(At, 1, 0); PG8_STAGE(PG8_SA(0, 1), a2 + hstep, voffA);
;             PG8_WAIT_V(8); PG8_WAIT_L(0); PG8_BAR; PG8_MMA(0, 0, At, B0); PG8_MMA(0, 1, At, B1); PG8_BAR; PG8_SCHED;
	s_add_i32 s58, 0, 0x18000
	s_add_i32 s59, 0, 0x1c000
	v_add_u32_e32 v156, s58, v149
	v_add_u32_e32 v172, s59, v149
	ds_read_b128 v[140:143], v156
	ds_read_b128 v[144:147], v156 offset:1024
	ds_read_b128 v[152:155], v156 offset:2048
	ds_read_b128 v[156:159], v156 offset:3072
	ds_read_b128 v[160:163], v172
	ds_read_b128 v[164:167], v172 offset:1024
	ds_read_b128 v[168:171], v172 offset:2048
	ds_read_b128 v[172:175], v172 offset:3072
	s_add_u32 s2, s52, 0x80000
	s_addc_u32 s3, s53, 0
	s_mov_b32 m0, s37
	v_lshl_add_u64 v[242:243], s[2:3], 0, v[130:131]
	ds_read_b128 v[176:179], v151 offset:32768
	ds_read_b128 v[180:183], v151 offset:33792
	ds_read_b128 v[200:203], v151 offset:34816
	ds_read_b128 v[204:207], v151 offset:35840
	ds_read_b128 v[208:211], v151 offset:36864
	ds_read_b128 v[212:215], v151 offset:37888
	ds_read_b128 v[216:219], v151 offset:38912
	ds_read_b128 v[232:235], v151 offset:39936
	global_load_lds_dwordx4 v[242:243], off
	v_lshl_add_u64 v[242:243], s[2:3], 0, v[132:133]
	s_mov_b32 m0, s38
	s_nop 0
	global_load_lds_dwordx4 v[242:243], off
	s_waitcnt vmcnt(8)
	s_waitcnt lgkmcnt(0)
	s_barrier
	s_nop 0
	s_waitcnt lgkmcnt(0)
	v_mfma_f32_16x16x32_bf16 v[126:129], v[140:143], v[176:179], v[126:129]
	v_mfma_f32_16x16x32_bf16 v[122:125], v[152:155], v[176:179], v[122:125]
	v_mfma_f32_16x16x32_bf16 v[110:113], v[140:143], v[200:203], v[110:113]
	v_mfma_f32_16x16x32_bf16 v[106:109], v[152:155], v[200:203], v[106:109]
	v_mfma_f32_16x16x32_bf16 v[94:97], v[140:143], v[208:211], v[94:97]
	v_mfma_f32_16x16x32_bf16 v[90:93], v[152:155], v[208:211], v[90:93]
	v_mfma_f32_16x16x32_bf16 v[78:81], v[140:143], v[216:219], v[78:81]
	v_mfma_f32_16x16x32_bf16 v[74:77], v[152:155], v[216:219], v[74:77]
	v_mfma_f32_16x16x32_bf16 v[126:129], v[144:147], v[180:183], v[126:129]
	v_mfma_f32_16x16x32_bf16 v[122:125], v[156:159], v[180:183], v[122:125]
	v_mfma_f32_16x16x32_bf16 v[110:113], v[144:147], v[204:207], v[110:113]
	v_mfma_f32_16x16x32_bf16 v[106:109], v[156:159], v[204:207], v[106:109]
	v_mfma_f32_16x16x32_bf16 v[94:97], v[144:147], v[212:215], v[94:97]
	v_mfma_f32_16x16x32_bf16 v[90:93], v[156:159], v[212:215], v[90:93]
	v_mfma_f32_16x16x32_bf16 v[78:81], v[144:147], v[232:235], v[78:81]
	v_mfma_f32_16x16x32_bf16 v[74:77], v[156:159], v[232:235], v[74:77]
	s_nop 0
	s_nop 0
	v_mfma_f32_16x16x32_bf16 v[118:121], v[160:163], v[176:179], v[118:121]
	v_mfma_f32_16x16x32_bf16 v[114:117], v[168:171], v[176:179], v[114:117]
	v_mfma_f32_16x16x32_bf16 v[102:105], v[160:163], v[200:203], v[102:105]
	v_mfma_f32_16x16x32_bf16 v[98:101], v[168:171], v[200:203], v[98:101]
	v_mfma_f32_16x16x32_bf16 v[86:89], v[160:163], v[208:211], v[86:89]
	v_mfma_f32_16x16x32_bf16 v[82:85], v[168:171], v[208:211], v[82:85]
	v_mfma_f32_16x16x32_bf16 v[70:73], v[160:163], v[216:219], v[70:73]
	v_mfma_f32_16x16x32_bf16 v[66:69], v[168:171], v[216:219], v[66:69]
	v_mfma_f32_16x16x32_bf16 v[118:121], v[164:167], v[180:183], v[118:121]
	v_mfma_f32_16x16x32_bf16 v[114:117], v[172:175], v[180:183], v[114:117]
	v_mfma_f32_16x16x32_bf16 v[102:105], v[164:167], v[204:207], v[102:105]
	v_mfma_f32_16x16x32_bf16 v[98:101], v[172:175], v[204:207], v[98:101]
	v_mfma_f32_16x16x32_bf16 v[86:89], v[164:167], v[212:215], v[86:89]
	v_mfma_f32_16x16x32_bf16 v[82:85], v[172:175], v[212:215], v[82:85]
	v_mfma_f32_16x16x32_bf16 v[70:73], v[164:167], v[232:235], v[70:73]
	v_mfma_f32_16x16x32_bf16 v[66:69], v[172:175], v[232:235], v[66:69]
	s_nop 0
	s_barrier
; #define PG8_STAGE(bufoff, gbase, voff) do { _Pragma("unroll") for (int _i = 0; _i < 2; ++_i) \
;         __builtin_amdgcn_global_load_lds((const unsigned*)((const char*)(gbase) + (voff)[_i]), (PG8_LAS unsigned*)(lds + (bufoff) + ldsw + _i * 8192), 16, 0, 0); } while (0)
; #define PG8_LDA(dst, b, h) do { _Pragma("unroll") for (int m = 0; m < 4; ++m) _Pragma("unroll") for (int k = 0; k < 2; ++k) dst[m][k] = *(const PG8_LAS bf16x8*)(lds + PG8_SA(b, h) + aoff + m * 2048 + k * 1024); } while (0)
; #define PG8_WAIT_V(n) asm volatile("s_waitcnt vmcnt(" #n ")" ::: "memory")
; template <class Epi, class Sched, bool ALIGN_EPI = false, bool SP2 = false>
; __device__ __forceinline__ void gemm_phase(PG8_LAS unsigned char* lds, const Gemm g, const Sched& S, const Epi& E) {
;     ...
;             PG8_LDA(At, 1, 1); PG8_STAGE(PG8_SB(1, 0), b3, voffB); PG8_STAGE(PG8_SB(1, 1), b3 + hstep, voffB); PG8_STAGE(PG8_SA(1, 0), a3, voffA);
;             PG8_WAIT_V(8); PG8_WAIT_L(0); PG8_BAR; PG8_MMA(1, 0, At, B0); PG8_MMA(1, 1, At, B1); PG8_BAR; PG8_SCHED;
;             } else {
;             PG8_LDB(B0, 0, 0); PG8_SCHED; PG8_LDA(At, 0, 0); PG8_STAGE(PG8_SA(1, 1), a1 + hstep, voffA);
;             PG8_WAIT_L(8); PG8_BAR; PG8_WAIT_L(0); PG8_MMA(0, 0, At, B0); PG8_BAR; PG8_SCHED;
;             PG8_LDB(B1, 0, 1); PG8_STAGE(PG8_SB(0, 0), b2, voffB);
;             PG8_BAR; PG8_WAIT_L(0); PG8_MMA(0, 1, At, B1); PG8_BAR;
;             PG8_LDA(At, 0, 1); PG8_STAGE(PG8_SA(0, 0), a2, voffA);
;             PG8_BAR; PG8_WAIT_L(0); PG8_MMA(1, 0, At, B0); PG8_BAR; PG8_SCHED;
;             PG8_STAGE(PG8_SB(0, 1), b2 + hstep, voffB);
;             PG8_WAIT_V(6); PG8_BAR; PG8_MMA(1, 1, At, B1); PG8_BAR;
;             PG8_LDB(B0, 1, 0); PG8_SCHED; PG8_LDA(At, 1, 0); PG8_STAGE(PG8_SA(0, 1), a2 + hstep, voffA);
;             PG8_WAIT_L(8); PG8_BAR; PG8_WAIT_L(0); PG8_MMA(0, 0, At, B0); PG8_BAR; PG8_SCHED;
;             PG8_LDB(B1, 1, 1); PG8_STAGE(PG8_SB(1, 0), b3, voffB);
;             PG8_BAR; PG8_WAIT_L(0); PG8_MMA(0, 1, At, B1); PG8_BAR;
;             PG8_LDA(At, 1, 1); PG8_STAGE(PG8_SA(1, 0), a3, voffA);
;             PG8_BAR; PG8_WAIT_L(0); PG8_MMA(1, 0, At, B0); PG8_BAR; PG8_SCHED;
;             PG8_STAGE(PG8_SB(1, 1), b3 + hstep, voffB);
;             PG8_WAIT_V(6); PG8_BAR; PG8_MMA(1, 1, At, B1); PG8_BAR;
;             }
;         }
;         if constexpr (ALIGN_EPI) { if (wr == 0) PG8_BAR; }
	s_add_i32 s2, s58, s33
	v_lshl_add_u64 v[184:185], v[184:185], 0, s[0:1]
	s_mov_b32 m0, s2
	ds_read_b128 v[176:179], v151 offset:49152
	ds_read_b128 v[180:183], v151 offset:50176
	ds_read_b128 v[200:203], v151 offset:51200
	ds_read_b128 v[204:207], v151 offset:52224
	ds_read_b128 v[208:211], v151 offset:53248
	ds_read_b128 v[212:215], v151 offset:54272
	ds_read_b128 v[216:219], v151 offset:55296
	ds_read_b128 v[232:235], v151 offset:56320
	global_load_lds_dwordx4 v[184:185], off
	s_add_i32 m0, s2, 0x2000
	s_add_u32 s2, s22, 0x80080
	v_lshl_add_u64 v[184:185], v[236:237], 0, s[0:1]
	s_addc_u32 s3, s23, 0
	s_add_i32 s22, s59, s33
	global_load_lds_dwordx4 v[184:185], off
	v_lshl_add_u64 v[184:185], s[2:3], 0, v[0:1]
	s_mov_b32 m0, s22
	s_nop 0
	global_load_lds_dwordx4 v[184:185], off
	v_lshl_add_u64 v[184:185], s[2:3], 0, v[134:135]
	s_add_i32 m0, s22, 0x2000
	s_nop 0
	global_load_lds_dwordx4 v[184:185], off
	v_lshl_add_u64 v[184:185], v[238:239], 0, s[0:1]
	s_mov_b32 m0, s49
	s_nop 0
	global_load_lds_dwordx4 v[184:185], off
	v_lshl_add_u64 v[184:185], v[240:241], 0, s[0:1]
	s_mov_b32 m0, s54
	s_nop 0
	global_load_lds_dwordx4 v[184:185], off
	s_waitcnt vmcnt(8)
	s_waitcnt lgkmcnt(0)
	s_barrier
	s_nop 0
	s_waitcnt lgkmcnt(0)
	v_mfma_f32_16x16x32_bf16 v[62:65], v[140:143], v[176:179], v[62:65]
	v_mfma_f32_16x16x32_bf16 v[58:61], v[152:155], v[176:179], v[58:61]
	v_mfma_f32_16x16x32_bf16 v[46:49], v[140:143], v[200:203], v[46:49]
	v_mfma_f32_16x16x32_bf16 v[42:45], v[152:155], v[200:203], v[42:45]
	v_mfma_f32_16x16x32_bf16 v[30:33], v[140:143], v[208:211], v[30:33]
	v_mfma_f32_16x16x32_bf16 v[26:29], v[152:155], v[208:211], v[26:29]
	v_mfma_f32_16x16x32_bf16 v[14:17], v[140:143], v[216:219], v[14:17]
	v_mfma_f32_16x16x32_bf16 v[10:13], v[152:155], v[216:219], v[10:13]
	v_mfma_f32_16x16x32_bf16 v[62:65], v[144:147], v[180:183], v[62:65]
	v_mfma_f32_16x16x32_bf16 v[58:61], v[156:159], v[180:183], v[58:61]
	v_mfma_f32_16x16x32_bf16 v[46:49], v[144:147], v[204:207], v[46:49]
	v_mfma_f32_16x16x32_bf16 v[42:45], v[156:159], v[204:207], v[42:45]
	v_mfma_f32_16x16x32_bf16 v[30:33], v[144:147], v[212:215], v[30:33]
	v_mfma_f32_16x16x32_bf16 v[26:29], v[156:159], v[212:215], v[26:29]
	v_mfma_f32_16x16x32_bf16 v[14:17], v[144:147], v[232:235], v[14:17]
	v_mfma_f32_16x16x32_bf16 v[10:13], v[156:159], v[232:235], v[10:13]
	s_nop 0
	s_nop 0
	v_mfma_f32_16x16x32_bf16 v[54:57], v[160:163], v[176:179], v[54:57]
	v_mfma_f32_16x16x32_bf16 v[50:53], v[168:171], v[176:179], v[50:53]
	v_mfma_f32_16x16x32_bf16 v[38:41], v[160:163], v[200:203], v[38:41]
	v_mfma_f32_16x16x32_bf16 v[34:37], v[168:171], v[200:203], v[34:37]
	v_mfma_f32_16x16x32_bf16 v[22:25], v[160:163], v[208:211], v[22:25]
	v_mfma_f32_16x16x32_bf16 v[18:21], v[168:171], v[208:211], v[18:21]
	v_mfma_f32_16x16x32_bf16 v[6:9], v[160:163], v[216:219], v[6:9]
	v_mfma_f32_16x16x32_bf16 v[2:5], v[168:171], v[216:219], v[2:5]
	v_mfma_f32_16x16x32_bf16 v[54:57], v[164:167], v[180:183], v[54:57]
	v_mfma_f32_16x16x32_bf16 v[50:53], v[172:175], v[180:183], v[50:53]
	v_mfma_f32_16x16x32_bf16 v[38:41], v[164:167], v[204:207], v[38:41]
	v_mfma_f32_16x16x32_bf16 v[34:37], v[172:175], v[204:207], v[34:37]
	v_mfma_f32_16x16x32_bf16 v[22:25], v[164:167], v[212:215], v[22:25]
	v_mfma_f32_16x16x32_bf16 v[18:21], v[172:175], v[212:215], v[18:21]
	v_mfma_f32_16x16x32_bf16 v[6:9], v[164:167], v[232:235], v[6:9]
	v_mfma_f32_16x16x32_bf16 v[2:5], v[172:175], v[232:235], v[2:5]
	s_nop 0
	s_barrier
	s_add_i32 s57, s57, 2
	s_add_u32 s43, s43, 0x100
	s_addc_u32 s56, s56, 0
	s_add_u32 s50, s50, 0x100
	s_addc_u32 s51, s51, 0
	s_cmp_gt_u32 s57, 29
	s_cbranch_scc0 .LBB0_118
	s_setprio 0
	s_and_b64 vcc, exec, s[16:17]
	s_cbranch_vccz .LBB0_121
	s_barrier

; __device__ __forceinline__ void lru_fix_tile(const Ctx& C, int l, int ct, int hd) {
;     ...
;         if (T.c == 63 && t == 127) { float* o2 = C.out + O_LRUP + (size_t)(l * 2 + T.sidx) * GW + chg;
;             *(f32x4*)o2 = (f32x4){h[0], h[1], h[2], h[3]}; *(f32x4*)(o2 + 4) = (f32x4){h[4], h[5], h[6], h[7]}; }
;     }
;     __syncthreads();
.LBB0_1243:
	s_or_b64 exec, exec, s[24:25]
	s_and_b64 s[2:3], s[62:63], s[60:61]
	s_and_saveexec_b64 s[24:25], s[2:3]
	s_cbranch_execz .LBB0_910
	s_add_u32 s2, s7, s22
	s_addc_u32 s3, s92, s23
	global_store_dwordx4 v58, v[6:9], s[2:3]
	global_store_dwordx4 v58, v[2:5], s[2:3] offset:16
	s_branch .LBB0_910
	s_nop 0
	s_nop 0
	s_nop 0
	s_nop 0
	s_nop 0
	s_nop 0
	s_nop 0
	s_nop 0
	s_nop 0
	s_nop 0
	s_nop 0
	s_nop 0

; #define PG8_STAGE(bufoff, gbase, voff) do { _Pragma("unroll") for (int _i = 0; _i < 2; ++_i) \
;         __builtin_amdgcn_global_load_lds((const unsigned*)((const char*)(gbase) + (voff)[_i]), (PG8_LAS unsigned*)(lds + (bufoff) + ldsw + _i * 8192), 16, 0, 0); } while (0)
; #define PG8_LDA(dst, b, h) do { _Pragma("unroll") for (int m = 0; m < 4; ++m) _Pragma("unroll") for (int k = 0; k < 2; ++k) dst[m][k] = *(const PG8_LAS bf16x8*)(lds + PG8_SA(b, h) + aoff + m * 2048 + k * 1024); } while (0)
; #define PG8_LDB(dst, b, h) do { _Pragma("unroll") for (int n = 0; n < 2; ++n) _Pragma("unroll") for (int k = 0; k < 2; ++k) dst[n][k] = *(const PG8_LAS bf16x8*)(lds + PG8_SB(b, h) + boff + n * 2048 + k * 1024); } while (0)
; #define PG8_WAIT_V(n) asm volatile("s_waitcnt vmcnt(" #n ")" ::: "memory")
; #define PG8_WAIT_L(n) asm volatile("s_waitcnt lgkmcnt(" #n ")" ::: "memory")
; #define PG8_BAR __builtin_amdgcn_s_barrier()
; #define PG8_SCHED __builtin_amdgcn_sched_barrier(0)
; template <class Epi, class Sched, bool ALIGN_EPI = false, bool SP2 = false>
; __device__ __forceinline__ void gemm_phase(PG8_LAS unsigned char* lds, const Gemm g, const Sched& S, const Epi& E) {
;     ...
;         const bool has_next = S.next(ui + 1, nxt);
;         const char* nA = has_next ? (const char*)g.A + (size_t)nxt.pm * tstep + (size_t)nxt.kt0 * kstep : cA; const char* nB = has_next ? (const char*)g.Bt + (size_t)nxt.pn * tstep + (size_t)nxt.kt0 * kstep : cB;
;         const int nt = cur.nkt;
;         for (int t = 0; t < nt; t += 2) {
;             const bool last = (t == nt - 2);
;             const char* a1 = cA + (size_t)(t + 1) * kstep;
;             const char* a2 = last ? nA : cA + (size_t)(t + 2) * kstep; const char* b2 = last ? nB : cB + (size_t)(t + 2) * kstep;
;             const char* a3 = a2 + kstep; const char* b3 = b2 + kstep;
;             if (last && has_next) S.a_ready(nxt);
;             if constexpr (SP2) {
;             PG8_LDB(B0, 0, 0); PG8_LDB(B1, 0, 1); PG8_SCHED; PG8_LDA(At, 0, 0); PG8_STAGE(PG8_SA(1, 1), a1 + hstep, voffA);
;             PG8_WAIT_V(8); PG8_WAIT_L(0); PG8_BAR; PG8_MMA(0, 0, At, B0); PG8_MMA(0, 1, At, B1); PG8_BAR; PG8_SCHED;
;             PG8_LDA(At, 0, 1); PG8_STAGE(PG8_SB(0, 0), b2, voffB); PG8_STAGE(PG8_SB(0, 1), b2 + hstep, voffB); PG8_STAGE(PG8_SA(0, 0), a2, voffA);
.LBB0_1333:
	s_add_i32 s2, s86, -2
	s_add_u32 s3, s22, 0x100
	s_addc_u32 s45, s23, 0
	s_add_u32 s22, s46, 0x80080
	s_addc_u32 s23, s47, 0
	s_mov_b32 s46, 0
	s_cmp_eq_u32 s60, 0
	s_cbranch_scc0 .Lmy_p5_prio_done
	s_setprio 1
.Lmy_p5_prio_done:
.LBB0_1334:
	s_add_i32 s63, s46, 2
	s_add_u32 s47, s22, 0xfff80080
	s_addc_u32 s65, s23, -1
	s_add_i32 s77, 0, 0x10000
	s_cmp_eq_u32 s2, s46
	s_cselect_b32 s83, s79, s65
	s_cselect_b32 s82, s78, s47
	v_add_u32_e32 v0, s77, v232
	s_cselect_b32 s47, s81, s45
	s_cselect_b32 s46, s80, s3
	s_add_i32 s65, 0, 0x14000
	s_waitcnt lgkmcnt(0)
	ds_read_b128 v[132:135], v0
	ds_read_b128 v[136:139], v0 offset:1024
	ds_read_b128 v[140:143], v0 offset:2048
	ds_read_b128 v[144:147], v0 offset:3072
	v_add_u32_e32 v0, s65, v232
	ds_read_b128 v[148:151], v0
	ds_read_b128 v[152:155], v0 offset:1024
	ds_read_b128 v[156:159], v0 offset:2048
	ds_read_b128 v[160:163], v0 offset:3072
	v_lshl_add_u64 v[2:3], s[22:23], 0, v[208:209]
	s_add_i32 m0, s35, 0xc000
	ds_read_b128 v[164:167], v234
	ds_read_b128 v[168:171], v234 offset:1024
	ds_read_b128 v[172:175], v234 offset:2048
	ds_read_b128 v[176:179], v234 offset:3072
	ds_read_b128 v[180:183], v234 offset:4096
	ds_read_b128 v[210:213], v234 offset:5120
	ds_read_b128 v[214:217], v234 offset:6144
	ds_read_b128 v[236:239], v234 offset:7168
	global_load_lds_dwordx4 v[2:3], off
	v_lshl_add_u64 v[2:3], s[22:23], 0, v[206:207]
	s_add_i32 m0, s35, 0xe000
	s_nop 0
	global_load_lds_dwordx4 v[2:3], off
	s_waitcnt vmcnt(8)
	s_waitcnt lgkmcnt(0)
	s_barrier
	s_nop 0
	s_waitcnt lgkmcnt(0)
	v_mfma_f32_16x16x32_bf16 v[128:131], v[132:135], v[164:167], v[128:131]
	v_mfma_f32_16x16x32_bf16 v[124:127], v[140:143], v[164:167], v[124:127]
	v_mfma_f32_16x16x32_bf16 v[120:123], v[132:135], v[172:175], v[120:123]
	v_mfma_f32_16x16x32_bf16 v[116:119], v[140:143], v[172:175], v[116:119]
	v_mfma_f32_16x16x32_bf16 v[112:115], v[132:135], v[180:183], v[112:115]
	v_mfma_f32_16x16x32_bf16 v[108:111], v[140:143], v[180:183], v[108:111]
	v_mfma_f32_16x16x32_bf16 v[104:107], v[132:135], v[214:217], v[104:107]
	v_mfma_f32_16x16x32_bf16 v[100:103], v[140:143], v[214:217], v[100:103]
	v_mfma_f32_16x16x32_bf16 v[128:131], v[136:139], v[168:171], v[128:131]
	v_mfma_f32_16x16x32_bf16 v[124:127], v[144:147], v[168:171], v[124:127]
	v_mfma_f32_16x16x32_bf16 v[120:123], v[136:139], v[176:179], v[120:123]
	v_mfma_f32_16x16x32_bf16 v[116:119], v[144:147], v[176:179], v[116:119]
	v_mfma_f32_16x16x32_bf16 v[112:115], v[136:139], v[210:213], v[112:115]
	v_mfma_f32_16x16x32_bf16 v[108:111], v[144:147], v[210:213], v[108:111]
	v_mfma_f32_16x16x32_bf16 v[104:107], v[136:139], v[236:239], v[104:107]
	v_mfma_f32_16x16x32_bf16 v[100:103], v[144:147], v[236:239], v[100:103]
	s_nop 0
	s_nop 0
	v_mfma_f32_16x16x32_bf16 v[96:99], v[148:151], v[164:167], v[96:99]
	v_mfma_f32_16x16x32_bf16 v[92:95], v[156:159], v[164:167], v[92:95]
	v_mfma_f32_16x16x32_bf16 v[88:91], v[148:151], v[172:175], v[88:91]
	v_mfma_f32_16x16x32_bf16 v[84:87], v[156:159], v[172:175], v[84:87]
	v_mfma_f32_16x16x32_bf16 v[80:83], v[148:151], v[180:183], v[80:83]
	v_mfma_f32_16x16x32_bf16 v[76:79], v[156:159], v[180:183], v[76:79]
	v_mfma_f32_16x16x32_bf16 v[72:75], v[148:151], v[214:217], v[72:75]
	v_mfma_f32_16x16x32_bf16 v[68:71], v[156:159], v[214:217], v[68:71]
	v_mfma_f32_16x16x32_bf16 v[96:99], v[152:155], v[168:171], v[96:99]
	v_mfma_f32_16x16x32_bf16 v[92:95], v[160:163], v[168:171], v[92:95]
	v_mfma_f32_16x16x32_bf16 v[88:91], v[152:155], v[176:179], v[88:91]
	v_mfma_f32_16x16x32_bf16 v[84:87], v[160:163], v[176:179], v[84:87]
	v_mfma_f32_16x16x32_bf16 v[80:83], v[152:155], v[210:213], v[80:83]
	v_mfma_f32_16x16x32_bf16 v[76:79], v[160:163], v[210:213], v[76:79]
	v_mfma_f32_16x16x32_bf16 v[72:75], v[152:155], v[236:239], v[72:75]
	v_mfma_f32_16x16x32_bf16 v[68:71], v[160:163], v[236:239], v[68:71]
	s_nop 0
	s_barrier
	s_add_i32 s77, s77, s33
	v_lshl_add_u64 v[218:219], s[46:47], 0, v[200:201]
	s_mov_b32 m0, s77
	ds_read_b128 v[164:167], v234 offset:16384
	ds_read_b128 v[168:171], v234 offset:17408
	ds_read_b128 v[172:175], v234 offset:18432
	ds_read_b128 v[176:179], v234 offset:19456
	ds_read_b128 v[180:183], v234 offset:20480
	ds_read_b128 v[210:213], v234 offset:21504
	ds_read_b128 v[214:217], v234 offset:22528
	ds_read_b128 v[236:239], v234 offset:23552
	global_load_lds_dwordx4 v[218:219], off
	s_add_i32 m0, s77, 0x2000
	s_add_u32 s92, s46, 0x80000
	v_lshl_add_u64 v[240:241], s[46:47], 0, v[204:205]
	s_addc_u32 s93, s47, 0
	s_add_i32 s65, s65, s33
	global_load_lds_dwordx4 v[240:241], off
	v_lshl_add_u64 v[2:3], s[92:93], 0, v[200:201]
	s_mov_b32 m0, s65
	v_lshl_add_u64 v[242:243], s[82:83], 0, v[184:185]
	global_load_lds_dwordx4 v[2:3], off
	v_lshl_add_u64 v[2:3], s[92:93], 0, v[204:205]
	s_add_i32 m0, s65, 0x2000
	v_lshl_add_u64 v[244:245], s[82:83], 0, v[202:203]
	global_load_lds_dwordx4 v[2:3], off
	s_mov_b32 m0, s35
	s_nop 0
	global_load_lds_dwordx4 v[242:243], off
	s_mov_b32 m0, s36
	s_nop 0
	global_load_lds_dwordx4 v[244:245], off
	s_waitcnt vmcnt(8)
	s_waitcnt lgkmcnt(0)
	s_barrier
; #define PG8_STAGE(bufoff, gbase, voff) do { _Pragma("unroll") for (int _i = 0; _i < 2; ++_i) \
;         __builtin_amdgcn_global_load_lds((const unsigned*)((const char*)(gbase) + (voff)[_i]), (PG8_LAS unsigned*)(lds + (bufoff) + ldsw + _i * 8192), 16, 0, 0); } while (0)
; #define PG8_LDA(dst, b, h) do { _Pragma("unroll") for (int m = 0; m < 4; ++m) _Pragma("unroll") for (int k = 0; k < 2; ++k) dst[m][k] = *(const PG8_LAS bf16x8*)(lds + PG8_SA(b, h) + aoff + m * 2048 + k * 1024); } while (0)
; #define PG8_LDB(dst, b, h) do { _Pragma("unroll") for (int n = 0; n < 2; ++n) _Pragma("unroll") for (int k = 0; k < 2; ++k) dst[n][k] = *(const PG8_LAS bf16x8*)(lds + PG8_SB(b, h) + boff + n * 2048 + k * 1024); } while (0)
; #define PG8_MMA(ai, bj, At, Bt) do { __builtin_amdgcn_s_setprio(1); _Pragma("unroll") for (int m = 0; m < 4; ++m) _Pragma("unroll") for (int n = 0; n < 2; ++n) _Pragma("unroll") for (int k = 0; k < 2; ++k) \
;         acc[ai][bj][m][n] = __builtin_amdgcn_mfma_f32_16x16x32_bf16(Bt[n][k], At[m][k], acc[ai][bj][m][n], 0, 0, 0); __builtin_amdgcn_s_setprio(0); } while (0)
; #define PG8_WAIT_V(n) asm volatile("s_waitcnt vmcnt(" #n ")" ::: "memory")
; #define PG8_WAIT_L(n) asm volatile("s_waitcnt lgkmcnt(" #n ")" ::: "memory")
; #define PG8_BAR __builtin_amdgcn_s_barrier()
; #define PG8_SCHED __builtin_amdgcn_sched_barrier(0)
; template <class Epi, class Sched, bool ALIGN_EPI = false, bool SP2 = false>
; __device__ __forceinline__ void gemm_phase(PG8_LAS unsigned char* lds, const Gemm g, const Sched& S, const Epi& E) {
;     ...
;             PG8_WAIT_V(8); PG8_WAIT_L(0); PG8_BAR; PG8_MMA(1, 0, At, B0); PG8_MMA(1, 1, At, B1); PG8_BAR; PG8_SCHED;
;             PG8_LDB(B0, 1, 0); PG8_LDB(B1, 1, 1); PG8_SCHED; PG8_LDA(At, 1, 0); PG8_STAGE(PG8_SA(0, 1), a2 + hstep, voffA);
;             PG8_WAIT_V(8); PG8_WAIT_L(0); PG8_BAR; PG8_MMA(0, 0, At, B0); PG8_MMA(0, 1, At, B1); PG8_BAR; PG8_SCHED;
	s_nop 0
	s_waitcnt lgkmcnt(0)
	v_mfma_f32_16x16x32_bf16 v[64:67], v[132:135], v[164:167], v[64:67]
	v_mfma_f32_16x16x32_bf16 v[60:63], v[140:143], v[164:167], v[60:63]
	v_mfma_f32_16x16x32_bf16 v[56:59], v[132:135], v[172:175], v[56:59]
	v_mfma_f32_16x16x32_bf16 v[52:55], v[140:143], v[172:175], v[52:55]
	v_mfma_f32_16x16x32_bf16 v[48:51], v[132:135], v[180:183], v[48:51]
	v_mfma_f32_16x16x32_bf16 v[44:47], v[140:143], v[180:183], v[44:47]
	v_mfma_f32_16x16x32_bf16 v[40:43], v[132:135], v[214:217], v[40:43]
	v_mfma_f32_16x16x32_bf16 v[36:39], v[140:143], v[214:217], v[36:39]
	v_mfma_f32_16x16x32_bf16 v[64:67], v[136:139], v[168:171], v[64:67]
	v_mfma_f32_16x16x32_bf16 v[60:63], v[144:147], v[168:171], v[60:63]
	v_mfma_f32_16x16x32_bf16 v[56:59], v[136:139], v[176:179], v[56:59]
	v_mfma_f32_16x16x32_bf16 v[52:55], v[144:147], v[176:179], v[52:55]
	v_mfma_f32_16x16x32_bf16 v[48:51], v[136:139], v[210:213], v[48:51]
	v_mfma_f32_16x16x32_bf16 v[44:47], v[144:147], v[210:213], v[44:47]
	v_mfma_f32_16x16x32_bf16 v[40:43], v[136:139], v[236:239], v[40:43]
	v_mfma_f32_16x16x32_bf16 v[36:39], v[144:147], v[236:239], v[36:39]
	s_nop 0
	s_nop 0
	v_mfma_f32_16x16x32_bf16 v[32:35], v[148:151], v[164:167], v[32:35]
	v_mfma_f32_16x16x32_bf16 v[28:31], v[156:159], v[164:167], v[28:31]
	v_mfma_f32_16x16x32_bf16 v[24:27], v[148:151], v[172:175], v[24:27]
	v_mfma_f32_16x16x32_bf16 v[20:23], v[156:159], v[172:175], v[20:23]
	v_mfma_f32_16x16x32_bf16 v[16:19], v[148:151], v[180:183], v[16:19]
	v_mfma_f32_16x16x32_bf16 v[12:15], v[156:159], v[180:183], v[12:15]
	v_mfma_f32_16x16x32_bf16 v[8:11], v[148:151], v[214:217], v[8:11]
	v_mfma_f32_16x16x32_bf16 v[2:5], v[156:159], v[214:217], v[4:7]
	v_mfma_f32_16x16x32_bf16 v[32:35], v[152:155], v[168:171], v[32:35]
	v_mfma_f32_16x16x32_bf16 v[28:31], v[160:163], v[168:171], v[28:31]
	v_mfma_f32_16x16x32_bf16 v[24:27], v[152:155], v[176:179], v[24:27]
	v_mfma_f32_16x16x32_bf16 v[20:23], v[160:163], v[176:179], v[20:23]
	v_mfma_f32_16x16x32_bf16 v[16:19], v[152:155], v[210:213], v[16:19]
	v_mfma_f32_16x16x32_bf16 v[12:15], v[160:163], v[210:213], v[12:15]
	v_mfma_f32_16x16x32_bf16 v[8:11], v[152:155], v[236:239], v[8:11]
	v_mfma_f32_16x16x32_bf16 v[2:5], v[160:163], v[236:239], v[2:5]
	s_nop 0
	s_barrier
	s_add_i32 s65, 0, 0x18000
	v_add_u32_e32 v0, s65, v232
	s_add_i32 s77, 0, 0x1c000
	ds_read_b128 v[132:135], v0
	ds_read_b128 v[136:139], v0 offset:1024
	ds_read_b128 v[140:143], v0 offset:2048
	ds_read_b128 v[144:147], v0 offset:3072
	v_add_u32_e32 v0, s77, v232
	ds_read_b128 v[148:151], v0
	ds_read_b128 v[152:155], v0 offset:1024
	ds_read_b128 v[156:159], v0 offset:2048
	ds_read_b128 v[160:163], v0 offset:3072
	s_add_u32 s82, s82, 0x80000
	s_addc_u32 s83, s83, 0
	s_mov_b32 m0, s37
	v_lshl_add_u64 v[6:7], s[82:83], 0, v[184:185]
	ds_read_b128 v[164:167], v234 offset:32768
	ds_read_b128 v[168:171], v234 offset:33792
	ds_read_b128 v[172:175], v234 offset:34816
	ds_read_b128 v[176:179], v234 offset:35840
	ds_read_b128 v[180:183], v234 offset:36864
	ds_read_b128 v[210:213], v234 offset:37888
	ds_read_b128 v[214:217], v234 offset:38912
	ds_read_b128 v[236:239], v234 offset:39936
	global_load_lds_dwordx4 v[6:7], off
	v_lshl_add_u64 v[6:7], s[82:83], 0, v[202:203]
	s_mov_b32 m0, s67
	s_nop 0
	global_load_lds_dwordx4 v[6:7], off
	s_waitcnt vmcnt(8)
	s_waitcnt lgkmcnt(0)
	s_barrier
	s_nop 0
	s_waitcnt lgkmcnt(0)
	v_mfma_f32_16x16x32_bf16 v[128:131], v[132:135], v[164:167], v[128:131]
	v_mfma_f32_16x16x32_bf16 v[124:127], v[140:143], v[164:167], v[124:127]
	v_mfma_f32_16x16x32_bf16 v[120:123], v[132:135], v[172:175], v[120:123]
	v_mfma_f32_16x16x32_bf16 v[116:119], v[140:143], v[172:175], v[116:119]
	v_mfma_f32_16x16x32_bf16 v[112:115], v[132:135], v[180:183], v[112:115]
	v_mfma_f32_16x16x32_bf16 v[108:111], v[140:143], v[180:183], v[108:111]
	v_mfma_f32_16x16x32_bf16 v[104:107], v[132:135], v[214:217], v[104:107]
	v_mfma_f32_16x16x32_bf16 v[100:103], v[140:143], v[214:217], v[100:103]
	v_mfma_f32_16x16x32_bf16 v[128:131], v[136:139], v[168:171], v[128:131]
	v_mfma_f32_16x16x32_bf16 v[124:127], v[144:147], v[168:171], v[124:127]
	v_mfma_f32_16x16x32_bf16 v[120:123], v[136:139], v[176:179], v[120:123]
	v_mfma_f32_16x16x32_bf16 v[116:119], v[144:147], v[176:179], v[116:119]
	v_mfma_f32_16x16x32_bf16 v[112:115], v[136:139], v[210:213], v[112:115]
	v_mfma_f32_16x16x32_bf16 v[108:111], v[144:147], v[210:213], v[108:111]
	v_mfma_f32_16x16x32_bf16 v[104:107], v[136:139], v[236:239], v[104:107]
	v_mfma_f32_16x16x32_bf16 v[100:103], v[144:147], v[236:239], v[100:103]
	s_nop 0
	s_nop 0
	v_mfma_f32_16x16x32_bf16 v[96:99], v[148:151], v[164:167], v[96:99]
	v_mfma_f32_16x16x32_bf16 v[92:95], v[156:159], v[164:167], v[92:95]
	v_mfma_f32_16x16x32_bf16 v[88:91], v[148:151], v[172:175], v[88:91]
	v_mfma_f32_16x16x32_bf16 v[84:87], v[156:159], v[172:175], v[84:87]
	v_mfma_f32_16x16x32_bf16 v[80:83], v[148:151], v[180:183], v[80:83]
	v_mfma_f32_16x16x32_bf16 v[76:79], v[156:159], v[180:183], v[76:79]
	v_mfma_f32_16x16x32_bf16 v[72:75], v[148:151], v[214:217], v[72:75]
	v_mfma_f32_16x16x32_bf16 v[68:71], v[156:159], v[214:217], v[68:71]
	v_mfma_f32_16x16x32_bf16 v[96:99], v[152:155], v[168:171], v[96:99]
	v_mfma_f32_16x16x32_bf16 v[92:95], v[160:163], v[168:171], v[92:95]
	v_mfma_f32_16x16x32_bf16 v[88:91], v[152:155], v[176:179], v[88:91]
	v_mfma_f32_16x16x32_bf16 v[84:87], v[160:163], v[176:179], v[84:87]
	v_mfma_f32_16x16x32_bf16 v[80:83], v[152:155], v[210:213], v[80:83]
	v_mfma_f32_16x16x32_bf16 v[76:79], v[160:163], v[210:213], v[76:79]
	v_mfma_f32_16x16x32_bf16 v[72:75], v[152:155], v[236:239], v[72:75]
	v_mfma_f32_16x16x32_bf16 v[68:71], v[160:163], v[236:239], v[68:71]
	s_nop 0
	s_barrier
; #define PG8_STAGE(bufoff, gbase, voff) do { _Pragma("unroll") for (int _i = 0; _i < 2; ++_i) \
;         __builtin_amdgcn_global_load_lds((const unsigned*)((const char*)(gbase) + (voff)[_i]), (PG8_LAS unsigned*)(lds + (bufoff) + ldsw + _i * 8192), 16, 0, 0); } while (0)
; #define PG8_LDA(dst, b, h) do { _Pragma("unroll") for (int m = 0; m < 4; ++m) _Pragma("unroll") for (int k = 0; k < 2; ++k) dst[m][k] = *(const PG8_LAS bf16x8*)(lds + PG8_SA(b, h) + aoff + m * 2048 + k * 1024); } while (0)
; #define PG8_WAIT_V(n) asm volatile("s_waitcnt vmcnt(" #n ")" ::: "memory")
; template <class Epi, class Sched, bool ALIGN_EPI = false, bool SP2 = false>
; __device__ __forceinline__ void gemm_phase(PG8_LAS unsigned char* lds, const Gemm g, const Sched& S, const Epi& E) {
;     ...
;             PG8_LDA(At, 1, 1); PG8_STAGE(PG8_SB(1, 0), b3, voffB); PG8_STAGE(PG8_SB(1, 1), b3 + hstep, voffB); PG8_STAGE(PG8_SA(1, 0), a3, voffA);
;             PG8_WAIT_V(8); PG8_WAIT_L(0); PG8_BAR; PG8_MMA(1, 0, At, B0); PG8_MMA(1, 1, At, B1); PG8_BAR; PG8_SCHED;
;             } else {
;             PG8_LDB(B0, 0, 0); PG8_SCHED; PG8_LDA(At, 0, 0); PG8_STAGE(PG8_SA(1, 1), a1 + hstep, voffA);
;             PG8_WAIT_L(8); PG8_BAR; PG8_WAIT_L(0); PG8_MMA(0, 0, At, B0); PG8_BAR; PG8_SCHED;
;             PG8_LDB(B1, 0, 1); PG8_STAGE(PG8_SB(0, 0), b2, voffB);
;             PG8_BAR; PG8_WAIT_L(0); PG8_MMA(0, 1, At, B1); PG8_BAR;
;             PG8_LDA(At, 0, 1); PG8_STAGE(PG8_SA(0, 0), a2, voffA);
;             PG8_BAR; PG8_WAIT_L(0); PG8_MMA(1, 0, At, B0); PG8_BAR; PG8_SCHED;
;             PG8_STAGE(PG8_SB(0, 1), b2 + hstep, voffB);
;             PG8_WAIT_V(6); PG8_BAR; PG8_MMA(1, 1, At, B1); PG8_BAR;
;             PG8_LDB(B0, 1, 0); PG8_SCHED; PG8_LDA(At, 1, 0); PG8_STAGE(PG8_SA(0, 1), a2 + hstep, voffA);
;             PG8_WAIT_L(8); PG8_BAR; PG8_WAIT_L(0); PG8_MMA(0, 0, At, B0); PG8_BAR; PG8_SCHED;
;             PG8_LDB(B1, 1, 1); PG8_STAGE(PG8_SB(1, 0), b3, voffB);
;             PG8_BAR; PG8_WAIT_L(0); PG8_MMA(0, 1, At, B1); PG8_BAR;
;             PG8_LDA(At, 1, 1); PG8_STAGE(PG8_SA(1, 0), a3, voffA);
;             PG8_BAR; PG8_WAIT_L(0); PG8_MMA(1, 0, At, B0); PG8_BAR; PG8_SCHED;
;             PG8_STAGE(PG8_SB(1, 1), b3 + hstep, voffB);
;             PG8_WAIT_V(6); PG8_BAR; PG8_MMA(1, 1, At, B1); PG8_BAR;
;             }
;         }
;         if constexpr (ALIGN_EPI) { if (wr == 0) PG8_BAR; }
	s_add_i32 s65, s65, s33
	v_lshl_add_u64 v[6:7], v[218:219], 0, s[0:1]
	s_mov_b32 m0, s65
	ds_read_b128 v[164:167], v234 offset:49152
	ds_read_b128 v[168:171], v234 offset:50176
	ds_read_b128 v[172:175], v234 offset:51200
	ds_read_b128 v[176:179], v234 offset:52224
	ds_read_b128 v[180:183], v234 offset:53248
	ds_read_b128 v[210:213], v234 offset:54272
	ds_read_b128 v[214:217], v234 offset:55296
	ds_read_b128 v[236:239], v234 offset:56320
	global_load_lds_dwordx4 v[6:7], off
	s_add_i32 m0, s65, 0x2000
	s_add_u32 s46, s46, 0x80080
	v_lshl_add_u64 v[6:7], v[240:241], 0, s[0:1]
	s_addc_u32 s47, s47, 0
	s_add_i32 s65, s77, s33
	global_load_lds_dwordx4 v[6:7], off
	v_lshl_add_u64 v[6:7], s[46:47], 0, v[200:201]
	s_mov_b32 m0, s65
	s_nop 0
	global_load_lds_dwordx4 v[6:7], off
	v_lshl_add_u64 v[6:7], s[46:47], 0, v[204:205]
	s_add_i32 m0, s65, 0x2000
	s_nop 0
	global_load_lds_dwordx4 v[6:7], off
	v_lshl_add_u64 v[6:7], v[242:243], 0, s[0:1]
	s_mov_b32 m0, s71
	s_nop 0
	global_load_lds_dwordx4 v[6:7], off
	v_lshl_add_u64 v[6:7], v[244:245], 0, s[0:1]
	s_mov_b32 m0, s89
	s_nop 0
	global_load_lds_dwordx4 v[6:7], off
	s_waitcnt vmcnt(8)
	s_waitcnt lgkmcnt(0)
	s_barrier
	s_nop 0
	s_waitcnt lgkmcnt(0)
	v_mfma_f32_16x16x32_bf16 v[64:67], v[132:135], v[164:167], v[64:67]
	v_mfma_f32_16x16x32_bf16 v[60:63], v[140:143], v[164:167], v[60:63]
	v_mfma_f32_16x16x32_bf16 v[56:59], v[132:135], v[172:175], v[56:59]
	v_mfma_f32_16x16x32_bf16 v[52:55], v[140:143], v[172:175], v[52:55]
	v_mfma_f32_16x16x32_bf16 v[48:51], v[132:135], v[180:183], v[48:51]
	v_mfma_f32_16x16x32_bf16 v[44:47], v[140:143], v[180:183], v[44:47]
	v_mfma_f32_16x16x32_bf16 v[40:43], v[132:135], v[214:217], v[40:43]
	v_mfma_f32_16x16x32_bf16 v[36:39], v[140:143], v[214:217], v[36:39]
	v_mfma_f32_16x16x32_bf16 v[64:67], v[136:139], v[168:171], v[64:67]
	v_mfma_f32_16x16x32_bf16 v[60:63], v[144:147], v[168:171], v[60:63]
	v_mfma_f32_16x16x32_bf16 v[56:59], v[136:139], v[176:179], v[56:59]
	v_mfma_f32_16x16x32_bf16 v[52:55], v[144:147], v[176:179], v[52:55]
	v_mfma_f32_16x16x32_bf16 v[48:51], v[136:139], v[210:213], v[48:51]
	v_mfma_f32_16x16x32_bf16 v[44:47], v[144:147], v[210:213], v[44:47]
	v_mfma_f32_16x16x32_bf16 v[40:43], v[136:139], v[236:239], v[40:43]
	v_mfma_f32_16x16x32_bf16 v[36:39], v[144:147], v[236:239], v[36:39]
	s_nop 0
	s_nop 0
	v_mfma_f32_16x16x32_bf16 v[32:35], v[148:151], v[164:167], v[32:35]
	v_mfma_f32_16x16x32_bf16 v[28:31], v[156:159], v[164:167], v[28:31]
	v_mfma_f32_16x16x32_bf16 v[24:27], v[148:151], v[172:175], v[24:27]
	v_mfma_f32_16x16x32_bf16 v[20:23], v[156:159], v[172:175], v[20:23]
	v_mfma_f32_16x16x32_bf16 v[16:19], v[148:151], v[180:183], v[16:19]
	v_mfma_f32_16x16x32_bf16 v[12:15], v[156:159], v[180:183], v[12:15]
	v_mfma_f32_16x16x32_bf16 v[6:9], v[148:151], v[214:217], v[8:11]
	v_mfma_f32_16x16x32_bf16 v[2:5], v[156:159], v[214:217], v[2:5]
	v_mfma_f32_16x16x32_bf16 v[32:35], v[152:155], v[168:171], v[32:35]
	v_mfma_f32_16x16x32_bf16 v[28:31], v[160:163], v[168:171], v[28:31]
	v_mfma_f32_16x16x32_bf16 v[24:27], v[152:155], v[176:179], v[24:27]
	v_mfma_f32_16x16x32_bf16 v[20:23], v[160:163], v[176:179], v[20:23]
	v_mfma_f32_16x16x32_bf16 v[16:19], v[152:155], v[210:213], v[16:19]
	v_mfma_f32_16x16x32_bf16 v[12:15], v[160:163], v[210:213], v[12:15]
	v_mfma_f32_16x16x32_bf16 v[8:11], v[152:155], v[236:239], v[6:9]
	v_mfma_f32_16x16x32_bf16 v[4:7], v[160:163], v[236:239], v[2:5]
	s_nop 0
	s_barrier
	s_add_u32 s3, s3, 0x100
	s_addc_u32 s45, s45, 0
	s_add_u32 s22, s22, 0x100
	s_addc_u32 s23, s23, 0
	s_cmp_ge_i32 s63, s86
	s_mov_b32 s46, s63
	s_cbranch_scc0 .LBB0_1334
	s_setprio 0
	s_and_b64 vcc, exec, s[60:61]
	s_cbranch_vccz .LBB0_1337
	s_barrier

; #define PG8_WAIT_V(n) asm volatile("s_waitcnt vmcnt(" #n ")" ::: "memory")
; #define PG8_BAR __builtin_amdgcn_s_barrier()
; template <class Epi, class Sched, bool ALIGN_EPI = false, bool SP2 = false>
; __device__ __forceinline__ void gemm_phase(PG8_LAS unsigned char* lds, const Gemm g, const Sched& S, const Epi& E) {
;     ...
;         const bool has_next = S.next(ui + 1, nxt);
;         const char* nA = has_next ? (const char*)g.A + (size_t)nxt.pm * tstep + (size_t)nxt.kt0 * kstep : cA; const char* nB = has_next ? (const char*)g.Bt + (size_t)nxt.pn * tstep + (size_t)nxt.kt0 * kstep : cB;
;     ...
;     PG8_WAIT_V(0);
;     if constexpr (!ALIGN_EPI) { if (wr == 0) PG8_BAR; }
;     PG8_BAR;
.LBB0_1400:
	s_ashr_i32 s63, s62, 31
	s_lshl_b64 s[2:3], s[62:63], 20
	s_add_u32 s45, s12, s2
	s_addc_u32 s63, s13, s3
	s_ashr_i32 s77, s76, 31
	s_lshl_b64 s[2:3], s[76:77], 7
	s_add_u32 s78, s45, s2
	s_addc_u32 s79, s63, s3
	s_and_b64 vcc, exec, s[42:43]
	s_mov_b64 s[80:81], s[22:23]
	s_cbranch_vccz .LBB0_1332
	s_branch .LBB0_1333
	s_nop 0
	s_nop 0
	s_nop 0
	s_nop 0
	s_nop 0
	s_nop 0
	s_nop 0
	s_nop 0
	s_nop 0
	s_nop 0
	s_nop 0
	s_nop 0
	s_nop 0
	s_nop 0
	s_nop 0
	s_nop 0
	s_nop 0
	s_nop 0
	s_nop 0
	s_nop 0
	s_nop 0
	s_nop 0
	s_nop 0
	s_nop 0
	s_nop 0
	s_nop 0
	s_nop 0
	s_nop 0
	s_nop 0
	s_nop 0
	s_nop 0
	s_nop 0
	s_nop 0
	s_nop 0
	s_nop 0
	s_nop 0
	s_nop 0
	s_nop 0
	s_nop 0
	s_nop 0
	s_nop 0
	s_nop 0
	s_nop 0
	s_nop 0
	s_nop 0
	s_nop 0
	s_nop 0
	s_nop 0
	s_nop 0
	s_nop 0
	s_nop 0
	s_nop 0
	s_nop 0
	s_nop 0
	s_nop 0
	s_nop 0
	s_nop 0
	s_nop 0
	s_nop 0
	s_nop 0
	s_nop 0
	s_nop 0
	s_nop 0
	s_nop 0
	s_nop 0
	s_nop 0
	s_nop 0
	s_nop 0
	s_nop 0
	s_nop 0
	s_nop 0
	s_nop 0
	s_nop 0
	s_nop 0
	s_nop 0
	s_nop 0
	s_nop 0
	s_nop 0
	s_nop 0
	s_nop 0
	s_nop 0
	s_nop 0
	s_nop 0
	s_nop 0
	s_nop 0
	s_nop 0
	s_nop 0
	s_nop 0
	s_nop 0
	s_nop 0
	s_nop 0
	s_nop 0
	s_nop 0
	s_nop 0
	s_nop 0
	s_nop 0
	s_nop 0
	s_nop 0
	s_nop 0
	s_nop 0
	s_nop 0
	s_nop 0
	s_nop 0
.LBB0_1408:
	s_waitcnt vmcnt(0)
	v_readlane_b32 s60, v250, 5
	v_readlane_b32 s90, v249, 49
	v_readlane_b32 s61, v250, 6
	v_readlane_b32 s71, v250, 0
	s_mov_b64 s[56:57], s[94:95]
	v_readlane_b32 s91, v249, 50
	s_barrier

; __device__ __forceinline__ unsigned pk2(float lo, float hi) { unsigned r; asm volatile("v_cvt_pk_bf16_f32 %0, %1, %2" : "=v"(r) : "v"(lo), "v"(hi)); return r; }
;     __device__ __forceinline__ void operator()(const f32x4 (&acc)[2][2][4][2], const Unit& u, int wr, int wc, int fr, int fq) const {
;         const int row0 = u.pm * BM + wr * 64 + fr, col0 = u.pn * HALF + wc * 32 + 8 * fq;
;         float rs[2][4];
; #pragma unroll
;         for (int ai = 0; ai < 2; ++ai)
; #pragma unroll
;             for (int m = 0; m < 4; ++m) rs[ai][m] = ssq[row0 + ai * HALF + m * 16];
; #pragma unroll
;         for (int ai = 0; ai < 2; ++ai)
; #pragma unroll
;             for (int m = 0; m < 4; ++m) { bf16_t* rowp = O + (size_t)(row0 + ai * HALF + m * 16) * DFF + col0; const float rsv = rsqrtf(rs[ai][m] * (1.f / D) + EPS);
;                 const float rs2 = rsv * rsv, nrs = -1.4426950409f * rsv;
;                 float v[8];
; #pragma unroll
;                 for (int n = 0; n < 2; ++n)
; #pragma unroll
;                     for (int j = 0; j < 4; ++j) {
;                         const float g0 = acc[ai][0][m][n][j], u0 = acc[ai][1][m][n][j];
;                         v[n * 4 + j] = (g0 * u0) * (rs2 * __builtin_amdgcn_rcpf(1.0f + __builtin_amdgcn_exp2f(g0 * nrs))); }
;                 u32x4 w; w.x = pk2(v[0], v[1]); w.y = pk2(v[2], v[3]); w.z = pk2(v[4], v[5]); w.w = pk2(v[6], v[7]);
;                 *(u32x4*)rowp = w; }
.LBB0_1490:
	v_lshl_add_u32 v144, s46, 8, v148
	v_ashrrev_i32_e32 v145, 31, v144
	v_lshl_add_u64 v[140:141], v[144:145], 2, s[12:13]
	flat_load_dword v146, v[140:141]
	flat_load_dword v164, v[140:141] offset:64
	flat_load_dword v162, v[140:141] offset:128
	flat_load_dword v160, v[140:141] offset:192
	flat_load_dword v158, v[140:141] offset:512
	flat_load_dword v156, v[140:141] offset:576
	flat_load_dword v154, v[140:141] offset:640
	flat_load_dword v152, v[140:141] offset:704
	v_mov_b32_e32 v166, v126
	v_lshl_or_b32 v142, s54, 7, v150
	v_ashrrev_i32_e32 v143, 31, v142
	v_mov_b64_e32 v[140:141], s[8:9]
	v_or_b32_e32 v165, 16, v144
	v_or_b32_e32 v163, 32, v144
	v_or_b32_e32 v161, 48, v144
	v_add_u32_e32 v159, 0x80, v144
	v_add_u32_e32 v157, 0x90, v144
	v_add_u32_e32 v155, 0xa0, v144
	v_add_u32_e32 v153, 0xb0, v144
	v_mad_i64_i32 v[144:145], s[2:3], v144, s34, v[140:141]
	s_mov_b64 s[22:23], -1
	s_mov_b64 s[56:57], s[94:95]
	s_waitcnt vmcnt(0) lgkmcnt(0)
	v_fmamk_f32 v146, v146, 0x3a000000, v223
	v_cmp_gt_f32_e32 vcc, s29, v146
	v_mul_f32_e32 v147, 0x4b800000, v146
	s_nop 0
	v_cndmask_b32_e32 v146, v146, v147, vcc
	v_rsq_f32_e32 v146, v146
	s_nop 0
	v_mul_f32_e32 v147, 0x45800000, v146
	v_cndmask_b32_e32 v146, v146, v147, vcc
	v_mul_f32_e32 v168, 0xbfb8aa3b, v146
	v_mul_f32_e32 v147, v146, v146
	v_mul_f32_e32 v146, v126, v168
	v_exp_f32_e32 v146, v146
	s_nop 0
	v_add_f32_e32 v146, 1.0, v146
	v_rcp_f32_e32 v167, v146
	v_mov_b32_e32 v146, v122
	v_mul_f32_e32 v122, v127, v168
	v_exp_f32_e32 v122, v122
	v_pk_mul_f32 v[166:167], v[146:147], v[166:167]
	v_mov_b32_e32 v146, v123
	v_mul_f32_e32 v126, v166, v167
	v_add_f32_e32 v122, 1.0, v122
	v_rcp_f32_e32 v167, v122
	v_mov_b32_e32 v166, v127
	v_pk_mul_f32 v[122:123], v[146:147], v[166:167]
	s_nop 0
	v_mul_f32_e32 v127, v122, v123
	v_mul_f32_e32 v122, v128, v168
	v_exp_f32_e32 v122, v122
	v_mov_b32_e32 v146, v124
	v_add_f32_e32 v122, 1.0, v122
	v_rcp_f32_e32 v123, v122
	v_mov_b32_e32 v122, v128
	v_pk_mul_f32 v[122:123], v[146:147], v[122:123]
	s_nop 0
	v_mul_f32_e32 v124, v122, v123
	v_mul_f32_e32 v122, v129, v168
	v_exp_f32_e32 v122, v122
	v_mov_b32_e32 v146, v125
	v_add_f32_e32 v122, 1.0, v122
	v_rcp_f32_e32 v123, v122
	v_mov_b32_e32 v122, v129
	v_pk_mul_f32 v[122:123], v[146:147], v[122:123]
	s_nop 0
	v_mul_f32_e32 v125, v122, v123
	v_mul_f32_e32 v122, v118, v168
	v_exp_f32_e32 v122, v122
	v_mov_b32_e32 v146, v114
	v_mul_f32_e32 v114, v119, v168
	v_exp_f32_e32 v114, v114
	v_add_f32_e32 v122, 1.0, v122
	v_rcp_f32_e32 v123, v122
	v_mov_b32_e32 v122, v118
	v_add_f32_e32 v114, 1.0, v114
	v_pk_mul_f32 v[122:123], v[146:147], v[122:123]
	s_nop 0
	v_mul_f32_e32 v118, v122, v123
	v_rcp_f32_e32 v123, v114
	v_mov_b32_e32 v146, v115
	v_mov_b32_e32 v122, v119
	v_pk_mul_f32 v[114:115], v[146:147], v[122:123]
	s_nop 0
	v_mul_f32_e32 v119, v114, v115
	v_mul_f32_e32 v114, v120, v168
	v_exp_f32_e32 v114, v114
	v_mov_b32_e32 v146, v116
	v_cvt_pk_bf16_f32 v116, v126, v127
	v_add_f32_e32 v114, 1.0, v114
	v_rcp_f32_e32 v115, v114
	v_mov_b32_e32 v114, v120
	v_pk_mul_f32 v[114:115], v[146:147], v[114:115]
	s_nop 0
	v_mul_f32_e32 v122, v114, v115
	v_mul_f32_e32 v114, v121, v168
	v_exp_f32_e32 v114, v114
	v_mov_b32_e32 v146, v117
	v_cvt_pk_bf16_f32 v117, v124, v125
	v_cvt_pk_bf16_f32 v118, v118, v119
	v_add_f32_e32 v114, 1.0, v114
	v_rcp_f32_e32 v115, v114
	v_mov_b32_e32 v114, v121
	v_pk_mul_f32 v[114:115], v[146:147], v[114:115]
	s_nop 0
	v_mul_f32_e32 v123, v114, v115
	v_lshlrev_b64 v[114:115], 1, v[142:143]
	v_lshl_add_u64 v[120:121], v[144:145], 0, v[114:115]
	v_cvt_pk_bf16_f32 v119, v122, v123
	flat_store_dwordx4 v[120:121], v[116:119]
	v_mov_b32_e32 v120, v110
	s_nop 0
	v_fmamk_f32 v118, v164, 0x3a000000, v223
	v_cmp_gt_f32_e32 vcc, s29, v118
	v_mul_f32_e32 v119, 0x4b800000, v118
	v_mad_i64_i32 v[116:117], s[2:3], v165, s34, v[140:141]
	v_cndmask_b32_e32 v118, v118, v119, vcc
	v_rsq_f32_e32 v118, v118
	s_nop 0
	v_mul_f32_e32 v119, 0x45800000, v118
	v_cndmask_b32_e32 v118, v118, v119, vcc
	v_mul_f32_e32 v122, 0xbfb8aa3b, v118
	v_mul_f32_e32 v119, v118, v118
	v_mul_f32_e32 v118, v110, v122
	v_exp_f32_e32 v118, v118
	s_nop 0
	v_add_f32_e32 v118, 1.0, v118
	v_rcp_f32_e32 v121, v118
	v_mov_b32_e32 v118, v106
	v_mul_f32_e32 v106, v111, v122
	v_exp_f32_e32 v106, v106
	v_pk_mul_f32 v[120:121], v[118:119], v[120:121]
	v_mov_b32_e32 v118, v107
	v_mul_f32_e32 v110, v120, v121
	v_add_f32_e32 v106, 1.0, v106
	v_rcp_f32_e32 v121, v106
	v_mov_b32_e32 v120, v111
	v_pk_mul_f32 v[106:107], v[118:119], v[120:121]
	s_nop 0
	v_mul_f32_e32 v111, v106, v107
	v_mul_f32_e32 v106, v112, v122
	v_exp_f32_e32 v106, v106
	v_mov_b32_e32 v118, v108
	v_add_f32_e32 v106, 1.0, v106
	v_rcp_f32_e32 v107, v106
	v_mov_b32_e32 v106, v112
	v_pk_mul_f32 v[106:107], v[118:119], v[106:107]
	s_nop 0
	v_mul_f32_e32 v108, v106, v107
	v_mul_f32_e32 v106, v113, v122
	v_exp_f32_e32 v106, v106
	v_mov_b32_e32 v118, v109
	v_add_f32_e32 v106, 1.0, v106
	v_rcp_f32_e32 v107, v106
	v_mov_b32_e32 v106, v113
	v_pk_mul_f32 v[106:107], v[118:119], v[106:107]
	s_nop 0
	v_mul_f32_e32 v109, v106, v107
	v_mul_f32_e32 v106, v102, v122
	v_exp_f32_e32 v106, v106
	v_mov_b32_e32 v118, v98
	v_mul_f32_e32 v98, v103, v122
	v_exp_f32_e32 v98, v98
	v_add_f32_e32 v106, 1.0, v106
	v_rcp_f32_e32 v107, v106
	v_mov_b32_e32 v106, v102
	v_add_f32_e32 v98, 1.0, v98
	v_pk_mul_f32 v[106:107], v[118:119], v[106:107]
	s_nop 0
	v_mul_f32_e32 v112, v106, v107
	v_rcp_f32_e32 v107, v98
	v_mov_b32_e32 v118, v99
	v_mov_b32_e32 v106, v103
	v_lshl_add_u64 v[102:103], v[116:117], 0, v[114:115]
	v_pk_mul_f32 v[98:99], v[118:119], v[106:107]
	v_mov_b32_e32 v118, v100
	v_mul_f32_e32 v106, v98, v99
; __device__ __forceinline__ unsigned pk2(float lo, float hi) { unsigned r; asm volatile("v_cvt_pk_bf16_f32 %0, %1, %2" : "=v"(r) : "v"(lo), "v"(hi)); return r; }
;     __device__ __forceinline__ void operator()(const f32x4 (&acc)[2][2][4][2], const Unit& u, int wr, int wc, int fr, int fq) const {
;     ...
;             for (int m = 0; m < 4; ++m) { bf16_t* rowp = O + (size_t)(row0 + ai * HALF + m * 16) * DFF + col0; const float rsv = rsqrtf(rs[ai][m] * (1.f / D) + EPS);
;                 const float rs2 = rsv * rsv, nrs = -1.4426950409f * rsv;
;                 float v[8];
; #pragma unroll
;                 for (int n = 0; n < 2; ++n)
; #pragma unroll
;                     for (int j = 0; j < 4; ++j) {
;                         const float g0 = acc[ai][0][m][n][j], u0 = acc[ai][1][m][n][j];
;                         v[n * 4 + j] = (g0 * u0) * (rs2 * __builtin_amdgcn_rcpf(1.0f + __builtin_amdgcn_exp2f(g0 * nrs))); }
;                 u32x4 w; w.x = pk2(v[0], v[1]); w.y = pk2(v[2], v[3]); w.z = pk2(v[4], v[5]); w.w = pk2(v[6], v[7]);
;                 *(u32x4*)rowp = w; }
	v_mul_f32_e32 v98, v104, v122
	v_exp_f32_e32 v98, v98
	s_nop 0
	v_add_f32_e32 v98, 1.0, v98
	v_rcp_f32_e32 v99, v98
	v_mov_b32_e32 v98, v104
	v_pk_mul_f32 v[98:99], v[118:119], v[98:99]
	s_nop 0
	v_mul_f32_e32 v104, v98, v99
	v_mul_f32_e32 v98, v105, v122
	v_exp_f32_e32 v98, v98
	v_mov_b32_e32 v118, v101
	v_add_f32_e32 v98, 1.0, v98
	v_rcp_f32_e32 v99, v98
	v_mov_b32_e32 v98, v105
	v_pk_mul_f32 v[98:99], v[118:119], v[98:99]
	s_nop 0
	v_mul_f32_e32 v101, v98, v99
	v_cvt_pk_bf16_f32 v98, v110, v111
	v_cvt_pk_bf16_f32 v99, v108, v109
	v_cvt_pk_bf16_f32 v100, v112, v106
	v_cvt_pk_bf16_f32 v101, v104, v101
	flat_store_dwordx4 v[102:103], v[98:101]
	v_mov_b32_e32 v102, v94
	s_nop 0
	v_fmamk_f32 v100, v162, 0x3a000000, v223
	v_cmp_gt_f32_e32 vcc, s29, v100
	v_mul_f32_e32 v101, 0x4b800000, v100
	v_mad_i64_i32 v[98:99], s[2:3], v163, s34, v[140:141]
	v_cndmask_b32_e32 v100, v100, v101, vcc
	v_rsq_f32_e32 v100, v100
	s_nop 0
	v_mul_f32_e32 v101, 0x45800000, v100
	v_cndmask_b32_e32 v100, v100, v101, vcc
	v_mul_f32_e32 v104, 0xbfb8aa3b, v100
	v_mul_f32_e32 v101, v100, v100
	v_mul_f32_e32 v100, v94, v104
	v_exp_f32_e32 v100, v100
	s_nop 0
	v_add_f32_e32 v100, 1.0, v100
	v_rcp_f32_e32 v103, v100
	v_mov_b32_e32 v100, v90
	v_mul_f32_e32 v90, v95, v104
	v_exp_f32_e32 v90, v90
	v_pk_mul_f32 v[102:103], v[100:101], v[102:103]
	v_mov_b32_e32 v100, v91
	v_mul_f32_e32 v94, v102, v103
	v_add_f32_e32 v90, 1.0, v90
	v_rcp_f32_e32 v103, v90
	v_mov_b32_e32 v102, v95
	v_pk_mul_f32 v[90:91], v[100:101], v[102:103]
	s_nop 0
	v_mul_f32_e32 v95, v90, v91
	v_mul_f32_e32 v90, v96, v104
	v_exp_f32_e32 v90, v90
	v_mov_b32_e32 v100, v92
	v_add_f32_e32 v90, 1.0, v90
	v_rcp_f32_e32 v91, v90
	v_mov_b32_e32 v90, v96
	v_pk_mul_f32 v[90:91], v[100:101], v[90:91]
	s_nop 0
	v_mul_f32_e32 v92, v90, v91
	v_mul_f32_e32 v90, v97, v104
	v_exp_f32_e32 v90, v90
	v_mov_b32_e32 v100, v93
	v_add_f32_e32 v90, 1.0, v90
	v_rcp_f32_e32 v91, v90
	v_mov_b32_e32 v90, v97
	v_pk_mul_f32 v[90:91], v[100:101], v[90:91]
	s_nop 0
	v_mul_f32_e32 v93, v90, v91
	v_mul_f32_e32 v90, v86, v104
	v_exp_f32_e32 v90, v90
	v_mov_b32_e32 v100, v82
	v_mul_f32_e32 v82, v87, v104
	v_exp_f32_e32 v82, v82
	v_add_f32_e32 v90, 1.0, v90
	v_rcp_f32_e32 v91, v90
	v_mov_b32_e32 v90, v86
	v_add_f32_e32 v82, 1.0, v82
	v_pk_mul_f32 v[90:91], v[100:101], v[90:91]
	s_nop 0
	v_mul_f32_e32 v96, v90, v91
	v_rcp_f32_e32 v91, v82
	v_mov_b32_e32 v100, v83
	v_mov_b32_e32 v90, v87
	v_lshl_add_u64 v[86:87], v[98:99], 0, v[114:115]
	v_pk_mul_f32 v[82:83], v[100:101], v[90:91]
	v_mov_b32_e32 v100, v84
	v_mul_f32_e32 v90, v82, v83
	v_mul_f32_e32 v82, v88, v104
	v_exp_f32_e32 v82, v82
	s_nop 0
	v_add_f32_e32 v82, 1.0, v82
	v_rcp_f32_e32 v83, v82
	v_mov_b32_e32 v82, v88
	v_pk_mul_f32 v[82:83], v[100:101], v[82:83]
	s_nop 0
	v_mul_f32_e32 v88, v82, v83
	v_mul_f32_e32 v82, v89, v104
	v_exp_f32_e32 v82, v82
	v_mov_b32_e32 v100, v85
	v_add_f32_e32 v82, 1.0, v82
	v_rcp_f32_e32 v83, v82
	v_mov_b32_e32 v82, v89
	v_pk_mul_f32 v[82:83], v[100:101], v[82:83]
	s_nop 0
	v_mul_f32_e32 v85, v82, v83
	v_cvt_pk_bf16_f32 v82, v94, v95
	v_cvt_pk_bf16_f32 v83, v92, v93
	v_cvt_pk_bf16_f32 v84, v96, v90
	v_cvt_pk_bf16_f32 v85, v88, v85
	flat_store_dwordx4 v[86:87], v[82:85]
	v_mov_b32_e32 v86, v78
	s_nop 0
	v_fmamk_f32 v84, v160, 0x3a000000, v223
	v_cmp_gt_f32_e32 vcc, s29, v84
	v_mul_f32_e32 v85, 0x4b800000, v84
	v_mad_i64_i32 v[82:83], s[2:3], v161, s34, v[140:141]
	v_cndmask_b32_e32 v84, v84, v85, vcc
	v_rsq_f32_e32 v84, v84
	s_nop 0
	v_mul_f32_e32 v85, 0x45800000, v84
	v_cndmask_b32_e32 v84, v84, v85, vcc
	v_mul_f32_e32 v88, 0xbfb8aa3b, v84
	v_mul_f32_e32 v85, v84, v84
	v_mul_f32_e32 v84, v78, v88
	v_exp_f32_e32 v84, v84
	s_nop 0
	v_add_f32_e32 v84, 1.0, v84
	v_rcp_f32_e32 v87, v84
	v_mov_b32_e32 v84, v74
	v_mul_f32_e32 v74, v79, v88
	v_exp_f32_e32 v74, v74
	v_pk_mul_f32 v[86:87], v[84:85], v[86:87]
	v_mov_b32_e32 v84, v75
	v_mul_f32_e32 v78, v86, v87
	v_add_f32_e32 v74, 1.0, v74
	v_rcp_f32_e32 v87, v74
	v_mov_b32_e32 v86, v79
	v_pk_mul_f32 v[74:75], v[84:85], v[86:87]
	s_nop 0
	v_mul_f32_e32 v79, v74, v75
	v_mul_f32_e32 v74, v80, v88
	v_exp_f32_e32 v74, v74
	v_mov_b32_e32 v84, v76
	v_add_f32_e32 v74, 1.0, v74
	v_rcp_f32_e32 v75, v74
	v_mov_b32_e32 v74, v80
	v_pk_mul_f32 v[74:75], v[84:85], v[74:75]
	s_nop 0
	v_mul_f32_e32 v76, v74, v75
	v_mul_f32_e32 v74, v81, v88
	v_exp_f32_e32 v74, v74
	v_mov_b32_e32 v84, v77
	v_add_f32_e32 v74, 1.0, v74
	v_rcp_f32_e32 v75, v74
	v_mov_b32_e32 v74, v81
	v_pk_mul_f32 v[74:75], v[84:85], v[74:75]
	s_nop 0
	v_mul_f32_e32 v77, v74, v75
	v_mul_f32_e32 v74, v70, v88
	v_exp_f32_e32 v74, v74
	v_mov_b32_e32 v84, v66
	v_mul_f32_e32 v66, v71, v88
	v_exp_f32_e32 v66, v66
	v_add_f32_e32 v74, 1.0, v74
	v_rcp_f32_e32 v75, v74
	v_mov_b32_e32 v74, v70
	v_add_f32_e32 v66, 1.0, v66
	v_pk_mul_f32 v[74:75], v[84:85], v[74:75]
	s_nop 0
	v_mul_f32_e32 v80, v74, v75
	v_rcp_f32_e32 v75, v66
	v_mov_b32_e32 v84, v67
	v_mov_b32_e32 v74, v71
	v_lshl_add_u64 v[70:71], v[82:83], 0, v[114:115]
	v_pk_mul_f32 v[66:67], v[84:85], v[74:75]
	v_mov_b32_e32 v84, v68
	v_mul_f32_e32 v74, v66, v67
	v_mul_f32_e32 v66, v72, v88
	v_exp_f32_e32 v66, v66
	s_nop 0
	v_add_f32_e32 v66, 1.0, v66
	v_rcp_f32_e32 v67, v66
	v_mov_b32_e32 v66, v72
	v_pk_mul_f32 v[66:67], v[84:85], v[66:67]
	s_nop 0
	v_mul_f32_e32 v72, v66, v67
	v_mul_f32_e32 v66, v73, v88
	v_exp_f32_e32 v66, v66
	v_mov_b32_e32 v84, v69
	v_add_f32_e32 v66, 1.0, v66
	v_rcp_f32_e32 v67, v66
	v_mov_b32_e32 v66, v73
	v_pk_mul_f32 v[66:67], v[84:85], v[66:67]
	s_nop 0
	v_mul_f32_e32 v69, v66, v67
	v_cvt_pk_bf16_f32 v66, v78, v79
	v_cvt_pk_bf16_f32 v67, v76, v77
	v_cvt_pk_bf16_f32 v68, v80, v74
	v_cvt_pk_bf16_f32 v69, v72, v69
; __device__ __forceinline__ unsigned pk2(float lo, float hi) { unsigned r; asm volatile("v_cvt_pk_bf16_f32 %0, %1, %2" : "=v"(r) : "v"(lo), "v"(hi)); return r; }
;     __device__ __forceinline__ void operator()(const f32x4 (&acc)[2][2][4][2], const Unit& u, int wr, int wc, int fr, int fq) const {
;     ...
;             for (int m = 0; m < 4; ++m) { bf16_t* rowp = O + (size_t)(row0 + ai * HALF + m * 16) * DFF + col0; const float rsv = rsqrtf(rs[ai][m] * (1.f / D) + EPS);
;                 const float rs2 = rsv * rsv, nrs = -1.4426950409f * rsv;
;                 float v[8];
; #pragma unroll
;                 for (int n = 0; n < 2; ++n)
; #pragma unroll
;                     for (int j = 0; j < 4; ++j) {
;                         const float g0 = acc[ai][0][m][n][j], u0 = acc[ai][1][m][n][j];
;                         v[n * 4 + j] = (g0 * u0) * (rs2 * __builtin_amdgcn_rcpf(1.0f + __builtin_amdgcn_exp2f(g0 * nrs))); }
;                 u32x4 w; w.x = pk2(v[0], v[1]); w.y = pk2(v[2], v[3]); w.z = pk2(v[4], v[5]); w.w = pk2(v[6], v[7]);
;                 *(u32x4*)rowp = w; }
	flat_store_dwordx4 v[70:71], v[66:69]
	v_mov_b32_e32 v70, v62
	s_nop 0
	v_fmamk_f32 v68, v158, 0x3a000000, v223
	v_cmp_gt_f32_e32 vcc, s29, v68
	v_mul_f32_e32 v69, 0x4b800000, v68
	v_mad_i64_i32 v[66:67], s[2:3], v159, s34, v[140:141]
	v_cndmask_b32_e32 v68, v68, v69, vcc
	v_rsq_f32_e32 v68, v68
	s_nop 0
	v_mul_f32_e32 v69, 0x45800000, v68
	v_cndmask_b32_e32 v68, v68, v69, vcc
	v_mul_f32_e32 v72, 0xbfb8aa3b, v68
	v_mul_f32_e32 v69, v68, v68
	v_mul_f32_e32 v68, v62, v72
	v_exp_f32_e32 v68, v68
	s_nop 0
	v_add_f32_e32 v68, 1.0, v68
	v_rcp_f32_e32 v71, v68
	v_mov_b32_e32 v68, v58
	v_mul_f32_e32 v58, v63, v72
	v_exp_f32_e32 v58, v58
	v_pk_mul_f32 v[70:71], v[68:69], v[70:71]
	v_mov_b32_e32 v68, v59
	v_mul_f32_e32 v62, v70, v71
	v_add_f32_e32 v58, 1.0, v58
	v_rcp_f32_e32 v71, v58
	v_mov_b32_e32 v70, v63
	v_pk_mul_f32 v[58:59], v[68:69], v[70:71]
	s_nop 0
	v_mul_f32_e32 v63, v58, v59
	v_mul_f32_e32 v58, v64, v72
	v_exp_f32_e32 v58, v58
	v_mov_b32_e32 v68, v60
	v_add_f32_e32 v58, 1.0, v58
	v_rcp_f32_e32 v59, v58
	v_mov_b32_e32 v58, v64
	v_pk_mul_f32 v[58:59], v[68:69], v[58:59]
	s_nop 0
	v_mul_f32_e32 v60, v58, v59
	v_mul_f32_e32 v58, v65, v72
	v_exp_f32_e32 v58, v58
	v_mov_b32_e32 v68, v61
	v_add_f32_e32 v58, 1.0, v58
	v_rcp_f32_e32 v59, v58
	v_mov_b32_e32 v58, v65
	v_pk_mul_f32 v[58:59], v[68:69], v[58:59]
	s_nop 0
	v_mul_f32_e32 v61, v58, v59
	v_mul_f32_e32 v58, v54, v72
	v_exp_f32_e32 v58, v58
	v_mov_b32_e32 v68, v50
	v_mul_f32_e32 v50, v55, v72
	v_exp_f32_e32 v50, v50
	v_add_f32_e32 v58, 1.0, v58
	v_rcp_f32_e32 v59, v58
	v_mov_b32_e32 v58, v54
	v_add_f32_e32 v50, 1.0, v50
	v_pk_mul_f32 v[58:59], v[68:69], v[58:59]
	s_nop 0
	v_mul_f32_e32 v64, v58, v59
	v_rcp_f32_e32 v59, v50
	v_mov_b32_e32 v68, v51
	v_mov_b32_e32 v58, v55
	v_lshl_add_u64 v[54:55], v[66:67], 0, v[114:115]
	v_pk_mul_f32 v[50:51], v[68:69], v[58:59]
	v_mov_b32_e32 v68, v52
	v_mul_f32_e32 v58, v50, v51
	v_mul_f32_e32 v50, v56, v72
	v_exp_f32_e32 v50, v50
	s_nop 0
	v_add_f32_e32 v50, 1.0, v50
	v_rcp_f32_e32 v51, v50
	v_mov_b32_e32 v50, v56
	v_pk_mul_f32 v[50:51], v[68:69], v[50:51]
	s_nop 0
	v_mul_f32_e32 v56, v50, v51
	v_mul_f32_e32 v50, v57, v72
	v_exp_f32_e32 v50, v50
	v_mov_b32_e32 v68, v53
	v_add_f32_e32 v50, 1.0, v50
	v_rcp_f32_e32 v51, v50
	v_mov_b32_e32 v50, v57
	v_pk_mul_f32 v[50:51], v[68:69], v[50:51]
	s_nop 0
	v_mul_f32_e32 v53, v50, v51
	v_cvt_pk_bf16_f32 v50, v62, v63
	v_cvt_pk_bf16_f32 v51, v60, v61
	v_cvt_pk_bf16_f32 v52, v64, v58
	v_cvt_pk_bf16_f32 v53, v56, v53
	flat_store_dwordx4 v[54:55], v[50:53]
	v_mov_b32_e32 v54, v46
	s_nop 0
	v_fmamk_f32 v52, v156, 0x3a000000, v223
	v_cmp_gt_f32_e32 vcc, s29, v52
	v_mul_f32_e32 v53, 0x4b800000, v52
	v_mad_i64_i32 v[50:51], s[2:3], v157, s34, v[140:141]
	v_cndmask_b32_e32 v52, v52, v53, vcc
	v_rsq_f32_e32 v52, v52
	s_nop 0
	v_mul_f32_e32 v53, 0x45800000, v52
	v_cndmask_b32_e32 v52, v52, v53, vcc
	v_mul_f32_e32 v56, 0xbfb8aa3b, v52
	v_mul_f32_e32 v53, v52, v52
	v_mul_f32_e32 v52, v46, v56
	v_exp_f32_e32 v52, v52
	s_nop 0
	v_add_f32_e32 v52, 1.0, v52
	v_rcp_f32_e32 v55, v52
	v_mov_b32_e32 v52, v42
	v_mul_f32_e32 v42, v47, v56
	v_exp_f32_e32 v42, v42
	v_pk_mul_f32 v[54:55], v[52:53], v[54:55]
	v_mov_b32_e32 v52, v43
	v_mul_f32_e32 v46, v54, v55
	v_add_f32_e32 v42, 1.0, v42
	v_rcp_f32_e32 v55, v42
	v_mov_b32_e32 v54, v47
	v_pk_mul_f32 v[42:43], v[52:53], v[54:55]
	s_nop 0
	v_mul_f32_e32 v47, v42, v43
	v_mul_f32_e32 v42, v48, v56
	v_exp_f32_e32 v42, v42
	v_mov_b32_e32 v52, v44
	v_add_f32_e32 v42, 1.0, v42
	v_rcp_f32_e32 v43, v42
	v_mov_b32_e32 v42, v48
	v_pk_mul_f32 v[42:43], v[52:53], v[42:43]
	s_nop 0
	v_mul_f32_e32 v44, v42, v43
	v_mul_f32_e32 v42, v49, v56
	v_exp_f32_e32 v42, v42
	v_mov_b32_e32 v52, v45
	v_add_f32_e32 v42, 1.0, v42
	v_rcp_f32_e32 v43, v42
	v_mov_b32_e32 v42, v49
	v_pk_mul_f32 v[42:43], v[52:53], v[42:43]
	s_nop 0
	v_mul_f32_e32 v45, v42, v43
	v_mul_f32_e32 v42, v38, v56
	v_exp_f32_e32 v42, v42
	v_mov_b32_e32 v52, v34
	v_mul_f32_e32 v34, v39, v56
	v_exp_f32_e32 v34, v34
	v_add_f32_e32 v42, 1.0, v42
	v_rcp_f32_e32 v43, v42
	v_mov_b32_e32 v42, v38
	v_add_f32_e32 v34, 1.0, v34
	v_pk_mul_f32 v[42:43], v[52:53], v[42:43]
	s_nop 0
	v_mul_f32_e32 v48, v42, v43
	v_rcp_f32_e32 v43, v34
	v_mov_b32_e32 v52, v35
	v_mov_b32_e32 v42, v39
	v_lshl_add_u64 v[38:39], v[50:51], 0, v[114:115]
	v_pk_mul_f32 v[34:35], v[52:53], v[42:43]
	v_mov_b32_e32 v52, v36
	v_mul_f32_e32 v42, v34, v35
	v_mul_f32_e32 v34, v40, v56
	v_exp_f32_e32 v34, v34
	s_nop 0
	v_add_f32_e32 v34, 1.0, v34
	v_rcp_f32_e32 v35, v34
	v_mov_b32_e32 v34, v40
	v_pk_mul_f32 v[34:35], v[52:53], v[34:35]
	s_nop 0
	v_mul_f32_e32 v40, v34, v35
	v_mul_f32_e32 v34, v41, v56
	v_exp_f32_e32 v34, v34
	v_mov_b32_e32 v52, v37
	v_add_f32_e32 v34, 1.0, v34
	v_rcp_f32_e32 v35, v34
	v_mov_b32_e32 v34, v41
	v_pk_mul_f32 v[34:35], v[52:53], v[34:35]
	s_nop 0
	v_mul_f32_e32 v37, v34, v35
	v_cvt_pk_bf16_f32 v34, v46, v47
	v_cvt_pk_bf16_f32 v35, v44, v45
	v_cvt_pk_bf16_f32 v36, v48, v42
	v_cvt_pk_bf16_f32 v37, v40, v37
	flat_store_dwordx4 v[38:39], v[34:37]
	v_mov_b32_e32 v38, v30
	s_nop 0
	v_fmamk_f32 v36, v154, 0x3a000000, v223
	v_cmp_gt_f32_e32 vcc, s29, v36
	v_mul_f32_e32 v37, 0x4b800000, v36
	v_mad_i64_i32 v[34:35], s[2:3], v155, s34, v[140:141]
; __device__ __forceinline__ unsigned pk2(float lo, float hi) { unsigned r; asm volatile("v_cvt_pk_bf16_f32 %0, %1, %2" : "=v"(r) : "v"(lo), "v"(hi)); return r; }
; #define PG8_WAIT_V(n) asm volatile("s_waitcnt vmcnt(" #n ")" ::: "memory")
; #define PG8_BAR __builtin_amdgcn_s_barrier()
; template <class Epi, class Sched, bool ALIGN_EPI = false, bool SP2 = false>
; __device__ __forceinline__ void gemm_phase(PG8_LAS unsigned char* lds, const Gemm g, const Sched& S, const Epi& E) {
;     ...
;         if (!has_next) break;
;         if (cur.ks != -2) {
; #pragma unroll
;         for (int a = 0; a < 2; ++a)
; #pragma unroll
;             for (int b = 0; b < 2; ++b)
; #pragma unroll
;                 for (int m = 0; m < 4; ++m)
; #pragma unroll
;                     for (int n = 0; n < 2; ++n) acc[a][b][m][n] = (f32x4){0.f, 0.f, 0.f, 0.f};
;         }
;         cur = nxt; cA = nA; cB = nB; ++ui;
;         if constexpr (ALIGN_EPI) { if (wr == 1) PG8_BAR; }
;     }
;     PG8_WAIT_V(0);
;     if constexpr (!ALIGN_EPI) { if (wr == 0) PG8_BAR; }
;     PG8_BAR;
;     __device__ __forceinline__ void operator()(const f32x4 (&acc)[2][2][4][2], const Unit& u, int wr, int wc, int fr, int fq) const {
;     ...
;             for (int m = 0; m < 4; ++m) { bf16_t* rowp = O + (size_t)(row0 + ai * HALF + m * 16) * DFF + col0; const float rsv = rsqrtf(rs[ai][m] * (1.f / D) + EPS);
;                 const float rs2 = rsv * rsv, nrs = -1.4426950409f * rsv;
;                 float v[8];
; #pragma unroll
;                 for (int n = 0; n < 2; ++n)
; #pragma unroll
;                     for (int j = 0; j < 4; ++j) {
;                         const float g0 = acc[ai][0][m][n][j], u0 = acc[ai][1][m][n][j];
;                         v[n * 4 + j] = (g0 * u0) * (rs2 * __builtin_amdgcn_rcpf(1.0f + __builtin_amdgcn_exp2f(g0 * nrs))); }
;                 u32x4 w; w.x = pk2(v[0], v[1]); w.y = pk2(v[2], v[3]); w.z = pk2(v[4], v[5]); w.w = pk2(v[6], v[7]);
;                 *(u32x4*)rowp = w; }
	v_cndmask_b32_e32 v36, v36, v37, vcc
	v_rsq_f32_e32 v36, v36
	s_nop 0
	v_mul_f32_e32 v37, 0x45800000, v36
	v_cndmask_b32_e32 v36, v36, v37, vcc
	v_mul_f32_e32 v40, 0xbfb8aa3b, v36
	v_mul_f32_e32 v37, v36, v36
	v_mul_f32_e32 v36, v30, v40
	v_exp_f32_e32 v36, v36
	s_nop 0
	v_add_f32_e32 v36, 1.0, v36
	v_rcp_f32_e32 v39, v36
	v_mov_b32_e32 v36, v26
	v_mul_f32_e32 v26, v31, v40
	v_exp_f32_e32 v26, v26
	v_pk_mul_f32 v[38:39], v[36:37], v[38:39]
	v_mov_b32_e32 v36, v27
	v_mul_f32_e32 v30, v38, v39
	v_add_f32_e32 v26, 1.0, v26
	v_rcp_f32_e32 v39, v26
	v_mov_b32_e32 v38, v31
	v_pk_mul_f32 v[26:27], v[36:37], v[38:39]
	s_nop 0
	v_mul_f32_e32 v31, v26, v27
	v_mul_f32_e32 v26, v32, v40
	v_exp_f32_e32 v26, v26
	v_mov_b32_e32 v36, v28
	v_add_f32_e32 v26, 1.0, v26
	v_rcp_f32_e32 v27, v26
	v_mov_b32_e32 v26, v32
	v_pk_mul_f32 v[26:27], v[36:37], v[26:27]
	s_nop 0
	v_mul_f32_e32 v28, v26, v27
	v_mul_f32_e32 v26, v33, v40
	v_exp_f32_e32 v26, v26
	v_mov_b32_e32 v36, v29
	v_add_f32_e32 v26, 1.0, v26
	v_rcp_f32_e32 v27, v26
	v_mov_b32_e32 v26, v33
	v_pk_mul_f32 v[26:27], v[36:37], v[26:27]
	s_nop 0
	v_mul_f32_e32 v29, v26, v27
	v_mul_f32_e32 v26, v22, v40
	v_exp_f32_e32 v26, v26
	v_mov_b32_e32 v36, v18
	v_mul_f32_e32 v18, v23, v40
	v_exp_f32_e32 v18, v18
	v_add_f32_e32 v26, 1.0, v26
	v_rcp_f32_e32 v27, v26
	v_mov_b32_e32 v26, v22
	v_add_f32_e32 v18, 1.0, v18
	v_pk_mul_f32 v[26:27], v[36:37], v[26:27]
	s_nop 0
	v_mul_f32_e32 v32, v26, v27
	v_rcp_f32_e32 v27, v18
	v_mov_b32_e32 v36, v19
	v_mov_b32_e32 v26, v23
	v_lshl_add_u64 v[22:23], v[34:35], 0, v[114:115]
	v_pk_mul_f32 v[18:19], v[36:37], v[26:27]
	v_mov_b32_e32 v36, v20
	v_mul_f32_e32 v26, v18, v19
	v_mul_f32_e32 v18, v24, v40
	v_exp_f32_e32 v18, v18
	s_nop 0
	v_add_f32_e32 v18, 1.0, v18
	v_rcp_f32_e32 v19, v18
	v_mov_b32_e32 v18, v24
	v_pk_mul_f32 v[18:19], v[36:37], v[18:19]
	s_nop 0
	v_mul_f32_e32 v24, v18, v19
	v_mul_f32_e32 v18, v25, v40
	v_exp_f32_e32 v18, v18
	v_mov_b32_e32 v36, v21
	v_add_f32_e32 v18, 1.0, v18
	v_rcp_f32_e32 v19, v18
	v_mov_b32_e32 v18, v25
	v_pk_mul_f32 v[18:19], v[36:37], v[18:19]
	s_nop 0
	v_mul_f32_e32 v21, v18, v19
	v_cvt_pk_bf16_f32 v18, v30, v31
	v_cvt_pk_bf16_f32 v19, v28, v29
	v_cvt_pk_bf16_f32 v20, v32, v26
	v_cvt_pk_bf16_f32 v21, v24, v21
	flat_store_dwordx4 v[22:23], v[18:21]
	v_mov_b32_e32 v22, v14
	s_nop 0
	v_fmamk_f32 v20, v152, 0x3a000000, v223
	v_cmp_gt_f32_e32 vcc, s29, v20
	v_mul_f32_e32 v21, 0x4b800000, v20
	v_mad_i64_i32 v[18:19], s[2:3], v153, s34, v[140:141]
	v_cndmask_b32_e32 v20, v20, v21, vcc
	v_rsq_f32_e32 v20, v20
	s_nop 0
	v_mul_f32_e32 v21, 0x45800000, v20
	v_cndmask_b32_e32 v20, v20, v21, vcc
	v_mul_f32_e32 v24, 0xbfb8aa3b, v20
	v_mul_f32_e32 v21, v20, v20
	v_mul_f32_e32 v20, v14, v24
	v_exp_f32_e32 v20, v20
	s_andn2_b64 vcc, exec, s[40:41]
	v_add_f32_e32 v20, 1.0, v20
	v_rcp_f32_e32 v23, v20
	v_mov_b32_e32 v20, v10
	v_mul_f32_e32 v10, v15, v24
	v_exp_f32_e32 v10, v10
	v_pk_mul_f32 v[22:23], v[20:21], v[22:23]
	v_mov_b32_e32 v20, v11
	v_mul_f32_e32 v14, v22, v23
	v_add_f32_e32 v10, 1.0, v10
	v_rcp_f32_e32 v23, v10
	v_mov_b32_e32 v22, v15
	v_pk_mul_f32 v[10:11], v[20:21], v[22:23]
	s_nop 0
	v_mul_f32_e32 v15, v10, v11
	v_mul_f32_e32 v10, v16, v24
	v_exp_f32_e32 v10, v10
	v_mov_b32_e32 v20, v12
	v_add_f32_e32 v10, 1.0, v10
	v_rcp_f32_e32 v11, v10
	v_mov_b32_e32 v10, v16
	v_pk_mul_f32 v[10:11], v[20:21], v[10:11]
	s_nop 0
	v_mul_f32_e32 v12, v10, v11
	v_mul_f32_e32 v10, v17, v24
	v_exp_f32_e32 v10, v10
	v_mov_b32_e32 v20, v13
	v_add_f32_e32 v10, 1.0, v10
	v_rcp_f32_e32 v11, v10
	v_mov_b32_e32 v10, v17
	v_pk_mul_f32 v[10:11], v[20:21], v[10:11]
	s_nop 0
	v_mul_f32_e32 v13, v10, v11
	v_mul_f32_e32 v10, v6, v24
	v_exp_f32_e32 v10, v10
	v_mov_b32_e32 v20, v2
	v_mul_f32_e32 v2, v7, v24
	v_exp_f32_e32 v2, v2
	v_add_f32_e32 v10, 1.0, v10
	v_rcp_f32_e32 v11, v10
	v_mov_b32_e32 v10, v6
	v_add_f32_e32 v2, 1.0, v2
	v_pk_mul_f32 v[10:11], v[20:21], v[10:11]
	s_nop 0
	v_mul_f32_e32 v16, v10, v11
	v_rcp_f32_e32 v11, v2
	v_mov_b32_e32 v20, v3
	v_mov_b32_e32 v10, v7
	v_lshl_add_u64 v[6:7], v[18:19], 0, v[114:115]
	v_pk_mul_f32 v[2:3], v[20:21], v[10:11]
	v_mov_b32_e32 v20, v4
	v_mul_f32_e32 v10, v2, v3
	v_mul_f32_e32 v2, v8, v24
	v_exp_f32_e32 v2, v2
	s_nop 0
	v_add_f32_e32 v2, 1.0, v2
	v_rcp_f32_e32 v3, v2
	v_mov_b32_e32 v2, v8
	v_pk_mul_f32 v[2:3], v[20:21], v[2:3]
	s_nop 0
	v_mul_f32_e32 v8, v2, v3
	v_mul_f32_e32 v2, v9, v24
	v_exp_f32_e32 v2, v2
	v_mov_b32_e32 v20, v5
	v_add_f32_e32 v2, 1.0, v2
	v_rcp_f32_e32 v3, v2
	v_mov_b32_e32 v2, v9
	v_pk_mul_f32 v[2:3], v[20:21], v[2:3]
	s_nop 0
	v_mul_f32_e32 v5, v2, v3
	v_cvt_pk_bf16_f32 v2, v14, v15
	v_cvt_pk_bf16_f32 v3, v12, v13
	v_cvt_pk_bf16_f32 v4, v16, v10
	v_cvt_pk_bf16_f32 v5, v8, v5
	flat_store_dwordx4 v[6:7], v[2:5]
	s_cbranch_vccnz .LBB0_1483
	s_andn2_b64 vcc, exec, s[14:15]
	s_cbranch_vccnz .LBB0_1482
	s_barrier
	s_branch .LBB0_1482
	s_nop 0
	s_nop 0
	s_nop 0
	s_nop 0
	s_nop 0
	s_nop 0
	s_nop 0
	s_nop 0
	s_nop 0
	s_nop 0
	s_nop 0
	s_nop 0
.LBB0_1493:
	s_waitcnt vmcnt(0)
	v_readlane_b32 s24, v250, 16
	v_readlane_b32 s36, v250, 18
	v_readlane_b32 s42, v250, 20
	v_readlane_b32 s40, v250, 22
	v_readlane_b32 s25, v250, 17
	v_readlane_b32 s37, v250, 19
	v_readlane_b32 s43, v250, 21
	v_readlane_b32 s41, v250, 23
	s_barrier

; #define PG8_STAGE(bufoff, gbase, voff) do { _Pragma("unroll") for (int _i = 0; _i < 2; ++_i) \
;         __builtin_amdgcn_global_load_lds((const unsigned*)((const char*)(gbase) + (voff)[_i]), (PG8_LAS unsigned*)(lds + (bufoff) + ldsw + _i * 8192), 16, 0, 0); } while (0)
; #define PG8_LDA(dst, b, h) do { _Pragma("unroll") for (int m = 0; m < 4; ++m) _Pragma("unroll") for (int k = 0; k < 2; ++k) dst[m][k] = *(const PG8_LAS bf16x8*)(lds + PG8_SA(b, h) + aoff + m * 2048 + k * 1024); } while (0)
; #define PG8_LDB(dst, b, h) do { _Pragma("unroll") for (int n = 0; n < 2; ++n) _Pragma("unroll") for (int k = 0; k < 2; ++k) dst[n][k] = *(const PG8_LAS bf16x8*)(lds + PG8_SB(b, h) + boff + n * 2048 + k * 1024); } while (0)
; #define PG8_WAIT_V(n) asm volatile("s_waitcnt vmcnt(" #n ")" ::: "memory")
; #define PG8_WAIT_L(n) asm volatile("s_waitcnt lgkmcnt(" #n ")" ::: "memory")
; #define PG8_BAR __builtin_amdgcn_s_barrier()
; #define PG8_SCHED __builtin_amdgcn_sched_barrier(0)
; template <class Epi, class Sched, bool ALIGN_EPI = false, bool SP2 = false>
; __device__ __forceinline__ void gemm_phase(PG8_LAS unsigned char* lds, const Gemm g, const Sched& S, const Epi& E) {
;     ...
;         const char* nA = has_next ? (const char*)g.A + (size_t)nxt.pm * tstep + (size_t)nxt.kt0 * kstep : cA; const char* nB = has_next ? (const char*)g.Bt + (size_t)nxt.pn * tstep + (size_t)nxt.kt0 * kstep : cB;
;         const int nt = cur.nkt;
;         for (int t = 0; t < nt; t += 2) {
;             const bool last = (t == nt - 2);
;             const char* a1 = cA + (size_t)(t + 1) * kstep;
;             const char* a2 = last ? nA : cA + (size_t)(t + 2) * kstep; const char* b2 = last ? nB : cB + (size_t)(t + 2) * kstep;
;             const char* a3 = a2 + kstep; const char* b3 = b2 + kstep;
;             if (last && has_next) S.a_ready(nxt);
;             if constexpr (SP2) {
;             PG8_LDB(B0, 0, 0); PG8_LDB(B1, 0, 1); PG8_SCHED; PG8_LDA(At, 0, 0); PG8_STAGE(PG8_SA(1, 1), a1 + hstep, voffA);
;             PG8_WAIT_V(8); PG8_WAIT_L(0); PG8_BAR; PG8_MMA(0, 0, At, B0); PG8_MMA(0, 1, At, B1); PG8_BAR; PG8_SCHED;
;     ...
;         for (int a = 0; a < 2; ++a)
; #pragma unroll
;             for (int b = 0; b < 2; ++b)
; #pragma unroll
;                 for (int m = 0; m < 4; ++m)
; #pragma unroll
;                     for (int n = 0; n < 2; ++n) acc[a][b][m][n] = (f32x4){0.f, 0.f, 0.f, 0.f};
.LBB0_1587:
	s_add_i32 s57, s83, -2
	s_add_u32 s86, s22, 0x100
	v_mov_b32_e32 v2, 0
	s_addc_u32 s87, s23, 0
	s_mov_b32 s2, 0
	v_mov_b32_e32 v3, v2
	v_mov_b32_e32 v4, v2
	v_mov_b32_e32 v5, v2
	v_mov_b32_e32 v6, v2
	v_mov_b32_e32 v7, v2
	v_mov_b32_e32 v8, v2
	v_mov_b32_e32 v9, v2
	v_mov_b32_e32 v10, v2
	v_mov_b32_e32 v11, v2
	v_mov_b32_e32 v12, v2
	v_mov_b32_e32 v13, v2
	v_mov_b32_e32 v14, v2
	v_mov_b32_e32 v15, v2
	v_mov_b32_e32 v16, v2
	v_mov_b32_e32 v17, v2
	v_mov_b32_e32 v26, v2
	v_mov_b32_e32 v27, v2
	v_mov_b32_e32 v28, v2
	v_mov_b32_e32 v29, v2
	v_mov_b32_e32 v30, v2
	v_mov_b32_e32 v31, v2
	v_mov_b32_e32 v32, v2
	v_mov_b32_e32 v33, v2
	s_waitcnt vmcnt(0)
	v_mov_b32_e32 v42, v2
	v_mov_b32_e32 v43, v2
	v_mov_b32_e32 v44, v2
	v_mov_b32_e32 v45, v2
	v_mov_b32_e32 v46, v2
	v_mov_b32_e32 v47, v2
	v_mov_b32_e32 v48, v2
	v_mov_b32_e32 v49, v2
	v_mov_b32_e32 v18, v2
	v_mov_b32_e32 v19, v2
	v_mov_b32_e32 v20, v2
	v_mov_b32_e32 v21, v2
	v_mov_b32_e32 v22, v2
	v_mov_b32_e32 v23, v2
	v_mov_b32_e32 v24, v2
	v_mov_b32_e32 v25, v2
	v_mov_b32_e32 v34, v2
	v_mov_b32_e32 v35, v2
	v_mov_b32_e32 v36, v2
	v_mov_b32_e32 v37, v2
	v_mov_b32_e32 v38, v2
	v_mov_b32_e32 v39, v2
	v_mov_b32_e32 v40, v2
	v_mov_b32_e32 v41, v2
	v_mov_b32_e32 v50, v2
	v_mov_b32_e32 v51, v2
	v_mov_b32_e32 v52, v2
	v_mov_b32_e32 v53, v2
	v_mov_b32_e32 v54, v2
	v_mov_b32_e32 v55, v2
	v_mov_b32_e32 v56, v2
	v_mov_b32_e32 v57, v2
	v_mov_b32_e32 v58, v2
	v_mov_b32_e32 v59, v2
	v_mov_b32_e32 v60, v2
	v_mov_b32_e32 v61, v2
	v_mov_b32_e32 v62, v2
	v_mov_b32_e32 v63, v2
	v_mov_b32_e32 v64, v2
	v_mov_b32_e32 v65, v2
	v_mov_b32_e32 v66, v2
	v_mov_b32_e32 v67, v2
	v_mov_b32_e32 v68, v2
	v_mov_b32_e32 v69, v2
	v_mov_b32_e32 v70, v2
	v_mov_b32_e32 v71, v2
	v_mov_b32_e32 v72, v2
	v_mov_b32_e32 v73, v2
	v_mov_b32_e32 v74, v2
	v_mov_b32_e32 v75, v2
	v_mov_b32_e32 v76, v2
	v_mov_b32_e32 v77, v2
	v_mov_b32_e32 v78, v2
	v_mov_b32_e32 v79, v2
	v_mov_b32_e32 v80, v2
	v_mov_b32_e32 v81, v2
	v_mov_b32_e32 v86, v2
	v_mov_b32_e32 v87, v2
	v_mov_b32_e32 v88, v2
	v_mov_b32_e32 v89, v2
	v_mov_b32_e32 v94, v2
	v_mov_b32_e32 v95, v2
	v_mov_b32_e32 v96, v2
	v_mov_b32_e32 v97, v2
	v_mov_b32_e32 v102, v2
	v_mov_b32_e32 v103, v2
	v_mov_b32_e32 v104, v2
	v_mov_b32_e32 v105, v2
	v_mov_b32_e32 v110, v2
	v_mov_b32_e32 v111, v2
	v_mov_b32_e32 v112, v2
	v_mov_b32_e32 v113, v2
	v_mov_b32_e32 v82, v2
	v_mov_b32_e32 v83, v2
	v_mov_b32_e32 v84, v2
	v_mov_b32_e32 v85, v2
	v_mov_b32_e32 v90, v2
	v_mov_b32_e32 v91, v2
	v_mov_b32_e32 v92, v2
	v_mov_b32_e32 v93, v2
	v_mov_b32_e32 v98, v2
	v_mov_b32_e32 v99, v2
	v_mov_b32_e32 v100, v2
	v_mov_b32_e32 v101, v2
	v_mov_b32_e32 v106, v2
	v_mov_b32_e32 v107, v2
	v_mov_b32_e32 v108, v2
	v_mov_b32_e32 v109, v2
	v_mov_b32_e32 v114, v2
	v_mov_b32_e32 v115, v2
	v_mov_b32_e32 v116, v2
	v_mov_b32_e32 v117, v2
	v_mov_b32_e32 v118, v2
	v_mov_b32_e32 v119, v2
	v_mov_b32_e32 v120, v2
	v_mov_b32_e32 v121, v2
	v_mov_b32_e32 v122, v2
	v_mov_b32_e32 v123, v2
	v_mov_b32_e32 v124, v2
	v_mov_b32_e32 v125, v2
	v_mov_b32_e32 v126, v2
	v_mov_b32_e32 v127, v2
	v_mov_b32_e32 v128, v2
	v_mov_b32_e32 v129, v2
	s_cmp_eq_u32 s54, 0
	s_cbranch_scc0 .Lmy_p8_prio_done
	s_setprio 1
.Lmy_p8_prio_done:
.LBB0_1588:
	s_add_i32 s3, s2, 2
	s_add_u32 s22, s46, 0x100
	s_addc_u32 s23, s47, 0
	s_add_i32 s88, 0, 0x10000
	s_cmp_eq_u32 s57, s2
	s_cselect_b32 s65, s59, s23
	s_cselect_b32 s64, s58, s22
	s_cselect_b32 s63, s61, s87
	s_cselect_b32 s62, s60, s86
	s_add_i32 s2, 0, 0x14000
	v_add_u32_e32 v142, s88, v232
	v_add_u32_e32 v158, s2, v232
	s_waitcnt lgkmcnt(0)
	ds_read_b128 v[130:133], v142
	ds_read_b128 v[134:137], v142 offset:1024
	ds_read_b128 v[138:141], v142 offset:2048
	ds_read_b128 v[142:145], v142 offset:3072
	ds_read_b128 v[146:149], v158
	ds_read_b128 v[150:153], v158 offset:1024
	ds_read_b128 v[154:157], v158 offset:2048
	ds_read_b128 v[158:161], v158 offset:3072
	v_lshl_add_u64 v[218:219], s[46:47], 0, v[208:209]
	s_add_i32 m0, s33, 0xc000
	ds_read_b128 v[162:165], v234
	ds_read_b128 v[166:169], v234 offset:1024
	ds_read_b128 v[170:173], v234 offset:2048
	ds_read_b128 v[174:177], v234 offset:3072
	ds_read_b128 v[178:181], v234 offset:4096
	ds_read_b128 v[182:185], v234 offset:5120
	ds_read_b128 v[210:213], v234 offset:6144
	ds_read_b128 v[214:217], v234 offset:7168
	global_load_lds_dwordx4 v[218:219], off
	v_lshl_add_u64 v[218:219], s[46:47], 0, v[206:207]
	s_add_i32 m0, s33, 0xe000
	s_nop 0
	global_load_lds_dwordx4 v[218:219], off
	s_waitcnt vmcnt(8)
	s_waitcnt lgkmcnt(0)
	s_barrier
; #define PG8_STAGE(bufoff, gbase, voff) do { _Pragma("unroll") for (int _i = 0; _i < 2; ++_i) \
;         __builtin_amdgcn_global_load_lds((const unsigned*)((const char*)(gbase) + (voff)[_i]), (PG8_LAS unsigned*)(lds + (bufoff) + ldsw + _i * 8192), 16, 0, 0); } while (0)
; #define PG8_LDA(dst, b, h) do { _Pragma("unroll") for (int m = 0; m < 4; ++m) _Pragma("unroll") for (int k = 0; k < 2; ++k) dst[m][k] = *(const PG8_LAS bf16x8*)(lds + PG8_SA(b, h) + aoff + m * 2048 + k * 1024); } while (0)
; #define PG8_MMA(ai, bj, At, Bt) do { __builtin_amdgcn_s_setprio(1); _Pragma("unroll") for (int m = 0; m < 4; ++m) _Pragma("unroll") for (int n = 0; n < 2; ++n) _Pragma("unroll") for (int k = 0; k < 2; ++k) \
;         acc[ai][bj][m][n] = __builtin_amdgcn_mfma_f32_16x16x32_bf16(Bt[n][k], At[m][k], acc[ai][bj][m][n], 0, 0, 0); __builtin_amdgcn_s_setprio(0); } while (0)
; #define PG8_WAIT_V(n) asm volatile("s_waitcnt vmcnt(" #n ")" ::: "memory")
; #define PG8_WAIT_L(n) asm volatile("s_waitcnt lgkmcnt(" #n ")" ::: "memory")
; #define PG8_BAR __builtin_amdgcn_s_barrier()
; #define PG8_SCHED __builtin_amdgcn_sched_barrier(0)
; template <class Epi, class Sched, bool ALIGN_EPI = false, bool SP2 = false>
; __device__ __forceinline__ void gemm_phase(PG8_LAS unsigned char* lds, const Gemm g, const Sched& S, const Epi& E) {
;     ...
;             PG8_WAIT_V(8); PG8_WAIT_L(0); PG8_BAR; PG8_MMA(0, 0, At, B0); PG8_MMA(0, 1, At, B1); PG8_BAR; PG8_SCHED;
;             PG8_LDA(At, 0, 1); PG8_STAGE(PG8_SB(0, 0), b2, voffB); PG8_STAGE(PG8_SB(0, 1), b2 + hstep, voffB); PG8_STAGE(PG8_SA(0, 0), a2, voffA);
;             PG8_WAIT_V(8); PG8_WAIT_L(0); PG8_BAR; PG8_MMA(1, 0, At, B0); PG8_MMA(1, 1, At, B1); PG8_BAR; PG8_SCHED;
	s_nop 0
	s_waitcnt lgkmcnt(0)
	v_mfma_f32_16x16x32_bf16 v[126:129], v[130:133], v[162:165], v[126:129]
	v_mfma_f32_16x16x32_bf16 v[122:125], v[138:141], v[162:165], v[122:125]
	v_mfma_f32_16x16x32_bf16 v[118:121], v[130:133], v[170:173], v[118:121]
	v_mfma_f32_16x16x32_bf16 v[114:117], v[138:141], v[170:173], v[114:117]
	v_mfma_f32_16x16x32_bf16 v[106:109], v[130:133], v[178:181], v[106:109]
	v_mfma_f32_16x16x32_bf16 v[98:101], v[138:141], v[178:181], v[98:101]
	v_mfma_f32_16x16x32_bf16 v[90:93], v[130:133], v[210:213], v[90:93]
	v_mfma_f32_16x16x32_bf16 v[82:85], v[138:141], v[210:213], v[82:85]
	v_mfma_f32_16x16x32_bf16 v[126:129], v[134:137], v[166:169], v[126:129]
	v_mfma_f32_16x16x32_bf16 v[122:125], v[142:145], v[166:169], v[122:125]
	v_mfma_f32_16x16x32_bf16 v[118:121], v[134:137], v[174:177], v[118:121]
	v_mfma_f32_16x16x32_bf16 v[114:117], v[142:145], v[174:177], v[114:117]
	v_mfma_f32_16x16x32_bf16 v[106:109], v[134:137], v[182:185], v[106:109]
	v_mfma_f32_16x16x32_bf16 v[98:101], v[142:145], v[182:185], v[98:101]
	v_mfma_f32_16x16x32_bf16 v[90:93], v[134:137], v[214:217], v[90:93]
	v_mfma_f32_16x16x32_bf16 v[82:85], v[142:145], v[214:217], v[82:85]
	s_nop 0
	s_nop 0
	v_mfma_f32_16x16x32_bf16 v[110:113], v[146:149], v[162:165], v[110:113]
	v_mfma_f32_16x16x32_bf16 v[102:105], v[154:157], v[162:165], v[102:105]
	v_mfma_f32_16x16x32_bf16 v[94:97], v[146:149], v[170:173], v[94:97]
	v_mfma_f32_16x16x32_bf16 v[86:89], v[154:157], v[170:173], v[86:89]
	v_mfma_f32_16x16x32_bf16 v[78:81], v[146:149], v[178:181], v[78:81]
	v_mfma_f32_16x16x32_bf16 v[74:77], v[154:157], v[178:181], v[74:77]
	v_mfma_f32_16x16x32_bf16 v[70:73], v[146:149], v[210:213], v[70:73]
	v_mfma_f32_16x16x32_bf16 v[66:69], v[154:157], v[210:213], v[66:69]
	v_mfma_f32_16x16x32_bf16 v[110:113], v[150:153], v[166:169], v[110:113]
	v_mfma_f32_16x16x32_bf16 v[102:105], v[158:161], v[166:169], v[102:105]
	v_mfma_f32_16x16x32_bf16 v[94:97], v[150:153], v[174:177], v[94:97]
	v_mfma_f32_16x16x32_bf16 v[86:89], v[158:161], v[174:177], v[86:89]
	v_mfma_f32_16x16x32_bf16 v[78:81], v[150:153], v[182:185], v[78:81]
	v_mfma_f32_16x16x32_bf16 v[74:77], v[158:161], v[182:185], v[74:77]
	v_mfma_f32_16x16x32_bf16 v[70:73], v[150:153], v[214:217], v[70:73]
	v_mfma_f32_16x16x32_bf16 v[66:69], v[158:161], v[214:217], v[66:69]
	s_nop 0
	s_barrier
	s_add_i32 s46, s88, s28
	v_lshl_add_u64 v[218:219], s[62:63], 0, v[0:1]
	s_mov_b32 m0, s46
	ds_read_b128 v[162:165], v234 offset:16384
	ds_read_b128 v[166:169], v234 offset:17408
	ds_read_b128 v[170:173], v234 offset:18432
	ds_read_b128 v[174:177], v234 offset:19456
	ds_read_b128 v[178:181], v234 offset:20480
	ds_read_b128 v[182:185], v234 offset:21504
	ds_read_b128 v[210:213], v234 offset:22528
	ds_read_b128 v[214:217], v234 offset:23552
	global_load_lds_dwordx4 v[218:219], off
	s_add_i32 m0, s46, 0x2000
	s_add_u32 s46, s62, 0x160000
	v_lshl_add_u64 v[236:237], s[62:63], 0, v[204:205]
	s_addc_u32 s47, s63, 0
	s_add_i32 s2, s2, s28
	global_load_lds_dwordx4 v[236:237], off
	v_lshl_add_u64 v[238:239], s[46:47], 0, v[0:1]
	s_mov_b32 m0, s2
	v_lshl_add_u64 v[240:241], s[64:65], 0, v[202:203]
	global_load_lds_dwordx4 v[238:239], off
	v_lshl_add_u64 v[238:239], s[46:47], 0, v[204:205]
	s_add_i32 m0, s2, 0x2000
	s_nop 0
	global_load_lds_dwordx4 v[238:239], off
	v_lshl_add_u64 v[238:239], s[64:65], 0, v[200:201]
	s_mov_b32 m0, s33
	s_nop 0
	global_load_lds_dwordx4 v[238:239], off
	s_mov_b32 m0, s35
	s_nop 0
	global_load_lds_dwordx4 v[240:241], off
	s_waitcnt vmcnt(8)
	s_waitcnt lgkmcnt(0)
	s_barrier
	s_nop 0
	s_waitcnt lgkmcnt(0)
	v_mfma_f32_16x16x32_bf16 v[62:65], v[130:133], v[162:165], v[62:65]
	v_mfma_f32_16x16x32_bf16 v[58:61], v[138:141], v[162:165], v[58:61]
	v_mfma_f32_16x16x32_bf16 v[54:57], v[130:133], v[170:173], v[54:57]
	v_mfma_f32_16x16x32_bf16 v[50:53], v[138:141], v[170:173], v[50:53]
	v_mfma_f32_16x16x32_bf16 v[38:41], v[130:133], v[178:181], v[38:41]
	v_mfma_f32_16x16x32_bf16 v[34:37], v[138:141], v[178:181], v[34:37]
	v_mfma_f32_16x16x32_bf16 v[22:25], v[130:133], v[210:213], v[22:25]
	v_mfma_f32_16x16x32_bf16 v[18:21], v[138:141], v[210:213], v[18:21]
	v_mfma_f32_16x16x32_bf16 v[62:65], v[134:137], v[166:169], v[62:65]
	v_mfma_f32_16x16x32_bf16 v[58:61], v[142:145], v[166:169], v[58:61]
	v_mfma_f32_16x16x32_bf16 v[54:57], v[134:137], v[174:177], v[54:57]
	v_mfma_f32_16x16x32_bf16 v[50:53], v[142:145], v[174:177], v[50:53]
	v_mfma_f32_16x16x32_bf16 v[38:41], v[134:137], v[182:185], v[38:41]
	v_mfma_f32_16x16x32_bf16 v[34:37], v[142:145], v[182:185], v[34:37]
	v_mfma_f32_16x16x32_bf16 v[22:25], v[134:137], v[214:217], v[22:25]
	v_mfma_f32_16x16x32_bf16 v[18:21], v[142:145], v[214:217], v[18:21]
	s_nop 0
	s_nop 0
	v_mfma_f32_16x16x32_bf16 v[46:49], v[146:149], v[162:165], v[46:49]
	v_mfma_f32_16x16x32_bf16 v[42:45], v[154:157], v[162:165], v[42:45]
	v_mfma_f32_16x16x32_bf16 v[30:33], v[146:149], v[170:173], v[30:33]
	v_mfma_f32_16x16x32_bf16 v[26:29], v[154:157], v[170:173], v[26:29]
	v_mfma_f32_16x16x32_bf16 v[14:17], v[146:149], v[178:181], v[14:17]
	v_mfma_f32_16x16x32_bf16 v[10:13], v[154:157], v[178:181], v[10:13]
	v_mfma_f32_16x16x32_bf16 v[6:9], v[146:149], v[210:213], v[6:9]
	v_mfma_f32_16x16x32_bf16 v[2:5], v[154:157], v[210:213], v[2:5]
	v_mfma_f32_16x16x32_bf16 v[46:49], v[150:153], v[166:169], v[46:49]
	v_mfma_f32_16x16x32_bf16 v[42:45], v[158:161], v[166:169], v[42:45]
	v_mfma_f32_16x16x32_bf16 v[30:33], v[150:153], v[174:177], v[30:33]
	v_mfma_f32_16x16x32_bf16 v[26:29], v[158:161], v[174:177], v[26:29]
	v_mfma_f32_16x16x32_bf16 v[14:17], v[150:153], v[182:185], v[14:17]
	v_mfma_f32_16x16x32_bf16 v[10:13], v[158:161], v[182:185], v[10:13]
	v_mfma_f32_16x16x32_bf16 v[6:9], v[150:153], v[214:217], v[6:9]
	v_mfma_f32_16x16x32_bf16 v[2:5], v[158:161], v[214:217], v[2:5]
	s_nop 0
	s_barrier
; #define PG8_STAGE(bufoff, gbase, voff) do { _Pragma("unroll") for (int _i = 0; _i < 2; ++_i) \
;         __builtin_amdgcn_global_load_lds((const unsigned*)((const char*)(gbase) + (voff)[_i]), (PG8_LAS unsigned*)(lds + (bufoff) + ldsw + _i * 8192), 16, 0, 0); } while (0)
; #define PG8_LDA(dst, b, h) do { _Pragma("unroll") for (int m = 0; m < 4; ++m) _Pragma("unroll") for (int k = 0; k < 2; ++k) dst[m][k] = *(const PG8_LAS bf16x8*)(lds + PG8_SA(b, h) + aoff + m * 2048 + k * 1024); } while (0)
; #define PG8_LDB(dst, b, h) do { _Pragma("unroll") for (int n = 0; n < 2; ++n) _Pragma("unroll") for (int k = 0; k < 2; ++k) dst[n][k] = *(const PG8_LAS bf16x8*)(lds + PG8_SB(b, h) + boff + n * 2048 + k * 1024); } while (0)
; #define PG8_MMA(ai, bj, At, Bt) do { __builtin_amdgcn_s_setprio(1); _Pragma("unroll") for (int m = 0; m < 4; ++m) _Pragma("unroll") for (int n = 0; n < 2; ++n) _Pragma("unroll") for (int k = 0; k < 2; ++k) \
;         acc[ai][bj][m][n] = __builtin_amdgcn_mfma_f32_16x16x32_bf16(Bt[n][k], At[m][k], acc[ai][bj][m][n], 0, 0, 0); __builtin_amdgcn_s_setprio(0); } while (0)
; #define PG8_WAIT_V(n) asm volatile("s_waitcnt vmcnt(" #n ")" ::: "memory")
; #define PG8_WAIT_L(n) asm volatile("s_waitcnt lgkmcnt(" #n ")" ::: "memory")
; #define PG8_BAR __builtin_amdgcn_s_barrier()
; #define PG8_SCHED __builtin_amdgcn_sched_barrier(0)
; template <class Epi, class Sched, bool ALIGN_EPI = false, bool SP2 = false>
; __device__ __forceinline__ void gemm_phase(PG8_LAS unsigned char* lds, const Gemm g, const Sched& S, const Epi& E) {
;     ...
;             PG8_LDB(B0, 1, 0); PG8_LDB(B1, 1, 1); PG8_SCHED; PG8_LDA(At, 1, 0); PG8_STAGE(PG8_SA(0, 1), a2 + hstep, voffA);
;             PG8_WAIT_V(8); PG8_WAIT_L(0); PG8_BAR; PG8_MMA(0, 0, At, B0); PG8_MMA(0, 1, At, B1); PG8_BAR; PG8_SCHED;
	s_add_i32 s2, 0, 0x18000
	s_add_i32 s88, 0, 0x1c000
	v_add_u32_e32 v142, s2, v232
	v_add_u32_e32 v158, s88, v232
	ds_read_b128 v[130:133], v142
	ds_read_b128 v[134:137], v142 offset:1024
	ds_read_b128 v[138:141], v142 offset:2048
	ds_read_b128 v[142:145], v142 offset:3072
	ds_read_b128 v[146:149], v158
	ds_read_b128 v[150:153], v158 offset:1024
	ds_read_b128 v[154:157], v158 offset:2048
	ds_read_b128 v[158:161], v158 offset:3072
	s_add_u32 s46, s64, 0x160000
	s_addc_u32 s47, s65, 0
	s_mov_b32 m0, s36
	v_lshl_add_u64 v[242:243], s[46:47], 0, v[200:201]
	ds_read_b128 v[162:165], v234 offset:32768
	ds_read_b128 v[166:169], v234 offset:33792
	ds_read_b128 v[170:173], v234 offset:34816
	ds_read_b128 v[174:177], v234 offset:35840
	ds_read_b128 v[178:181], v234 offset:36864
	ds_read_b128 v[182:185], v234 offset:37888
	ds_read_b128 v[210:213], v234 offset:38912
	ds_read_b128 v[214:217], v234 offset:39936
	global_load_lds_dwordx4 v[242:243], off
	v_lshl_add_u64 v[242:243], s[46:47], 0, v[202:203]
	s_mov_b32 m0, s37
	s_nop 0
	global_load_lds_dwordx4 v[242:243], off
	s_waitcnt vmcnt(8)
	s_waitcnt lgkmcnt(0)
	s_barrier
	s_nop 0
	s_waitcnt lgkmcnt(0)
	v_mfma_f32_16x16x32_bf16 v[126:129], v[130:133], v[162:165], v[126:129]
	v_mfma_f32_16x16x32_bf16 v[122:125], v[138:141], v[162:165], v[122:125]
	v_mfma_f32_16x16x32_bf16 v[118:121], v[130:133], v[170:173], v[118:121]
	v_mfma_f32_16x16x32_bf16 v[114:117], v[138:141], v[170:173], v[114:117]
	v_mfma_f32_16x16x32_bf16 v[106:109], v[130:133], v[178:181], v[106:109]
	v_mfma_f32_16x16x32_bf16 v[98:101], v[138:141], v[178:181], v[98:101]
	v_mfma_f32_16x16x32_bf16 v[90:93], v[130:133], v[210:213], v[90:93]
	v_mfma_f32_16x16x32_bf16 v[82:85], v[138:141], v[210:213], v[82:85]
	v_mfma_f32_16x16x32_bf16 v[126:129], v[134:137], v[166:169], v[126:129]
	v_mfma_f32_16x16x32_bf16 v[122:125], v[142:145], v[166:169], v[122:125]
	v_mfma_f32_16x16x32_bf16 v[118:121], v[134:137], v[174:177], v[118:121]
	v_mfma_f32_16x16x32_bf16 v[114:117], v[142:145], v[174:177], v[114:117]
	v_mfma_f32_16x16x32_bf16 v[106:109], v[134:137], v[182:185], v[106:109]
	v_mfma_f32_16x16x32_bf16 v[98:101], v[142:145], v[182:185], v[98:101]
	v_mfma_f32_16x16x32_bf16 v[90:93], v[134:137], v[214:217], v[90:93]
	v_mfma_f32_16x16x32_bf16 v[82:85], v[142:145], v[214:217], v[82:85]
	s_nop 0
	s_nop 0
	v_mfma_f32_16x16x32_bf16 v[110:113], v[146:149], v[162:165], v[110:113]
	v_mfma_f32_16x16x32_bf16 v[102:105], v[154:157], v[162:165], v[102:105]
	v_mfma_f32_16x16x32_bf16 v[94:97], v[146:149], v[170:173], v[94:97]
	v_mfma_f32_16x16x32_bf16 v[86:89], v[154:157], v[170:173], v[86:89]
	v_mfma_f32_16x16x32_bf16 v[78:81], v[146:149], v[178:181], v[78:81]
	v_mfma_f32_16x16x32_bf16 v[74:77], v[154:157], v[178:181], v[74:77]
	v_mfma_f32_16x16x32_bf16 v[70:73], v[146:149], v[210:213], v[70:73]
	v_mfma_f32_16x16x32_bf16 v[66:69], v[154:157], v[210:213], v[66:69]
	v_mfma_f32_16x16x32_bf16 v[110:113], v[150:153], v[166:169], v[110:113]
	v_mfma_f32_16x16x32_bf16 v[102:105], v[158:161], v[166:169], v[102:105]
	v_mfma_f32_16x16x32_bf16 v[94:97], v[150:153], v[174:177], v[94:97]
	v_mfma_f32_16x16x32_bf16 v[86:89], v[158:161], v[174:177], v[86:89]
	v_mfma_f32_16x16x32_bf16 v[78:81], v[150:153], v[182:185], v[78:81]
	v_mfma_f32_16x16x32_bf16 v[74:77], v[158:161], v[182:185], v[74:77]
	v_mfma_f32_16x16x32_bf16 v[70:73], v[150:153], v[214:217], v[70:73]
	v_mfma_f32_16x16x32_bf16 v[66:69], v[158:161], v[214:217], v[66:69]
	s_nop 0
	s_barrier
; #define PG8_STAGE(bufoff, gbase, voff) do { _Pragma("unroll") for (int _i = 0; _i < 2; ++_i) \
;         __builtin_amdgcn_global_load_lds((const unsigned*)((const char*)(gbase) + (voff)[_i]), (PG8_LAS unsigned*)(lds + (bufoff) + ldsw + _i * 8192), 16, 0, 0); } while (0)
; #define PG8_LDA(dst, b, h) do { _Pragma("unroll") for (int m = 0; m < 4; ++m) _Pragma("unroll") for (int k = 0; k < 2; ++k) dst[m][k] = *(const PG8_LAS bf16x8*)(lds + PG8_SA(b, h) + aoff + m * 2048 + k * 1024); } while (0)
; #define PG8_MMA(ai, bj, At, Bt) do { __builtin_amdgcn_s_setprio(1); _Pragma("unroll") for (int m = 0; m < 4; ++m) _Pragma("unroll") for (int n = 0; n < 2; ++n) _Pragma("unroll") for (int k = 0; k < 2; ++k) \
;         acc[ai][bj][m][n] = __builtin_amdgcn_mfma_f32_16x16x32_bf16(Bt[n][k], At[m][k], acc[ai][bj][m][n], 0, 0, 0); __builtin_amdgcn_s_setprio(0); } while (0)
; #define PG8_WAIT_V(n) asm volatile("s_waitcnt vmcnt(" #n ")" ::: "memory")
; #define PG8_WAIT_L(n) asm volatile("s_waitcnt lgkmcnt(" #n ")" ::: "memory")
; #define PG8_BAR __builtin_amdgcn_s_barrier()
; #define PG8_SCHED __builtin_amdgcn_sched_barrier(0)
; template <class Epi, class Sched, bool ALIGN_EPI = false, bool SP2 = false>
; __device__ __forceinline__ void gemm_phase(PG8_LAS unsigned char* lds, const Gemm g, const Sched& S, const Epi& E) {
;     ...
;             PG8_LDA(At, 1, 1); PG8_STAGE(PG8_SB(1, 0), b3, voffB); PG8_STAGE(PG8_SB(1, 1), b3 + hstep, voffB); PG8_STAGE(PG8_SA(1, 0), a3, voffA);
;             PG8_WAIT_V(8); PG8_WAIT_L(0); PG8_BAR; PG8_MMA(1, 0, At, B0); PG8_MMA(1, 1, At, B1); PG8_BAR; PG8_SCHED;
;     ...
;         }
;         if constexpr (ALIGN_EPI) { if (wr == 0) PG8_BAR; }
	s_add_i32 s2, s2, s28
	v_lshl_add_u64 v[218:219], v[218:219], 0, s[0:1]
	s_mov_b32 m0, s2
	ds_read_b128 v[162:165], v234 offset:49152
	ds_read_b128 v[166:169], v234 offset:50176
	ds_read_b128 v[170:173], v234 offset:51200
	ds_read_b128 v[174:177], v234 offset:52224
	ds_read_b128 v[178:181], v234 offset:53248
	ds_read_b128 v[182:185], v234 offset:54272
	ds_read_b128 v[210:213], v234 offset:55296
	ds_read_b128 v[214:217], v234 offset:56320
	global_load_lds_dwordx4 v[218:219], off
	s_add_i32 m0, s2, 0x2000
	s_add_u32 s46, s62, 0x160080
	v_lshl_add_u64 v[218:219], v[236:237], 0, s[0:1]
	s_addc_u32 s47, s63, 0
	s_add_i32 s2, s88, s28
	global_load_lds_dwordx4 v[218:219], off
	v_lshl_add_u64 v[218:219], s[46:47], 0, v[0:1]
	s_mov_b32 m0, s2
	s_nop 0
	global_load_lds_dwordx4 v[218:219], off
	v_lshl_add_u64 v[218:219], s[46:47], 0, v[204:205]
	s_add_i32 m0, s2, 0x2000
	s_nop 0
	global_load_lds_dwordx4 v[218:219], off
	v_lshl_add_u64 v[218:219], v[238:239], 0, s[0:1]
	s_mov_b32 m0, s71
	s_nop 0
	global_load_lds_dwordx4 v[218:219], off
	v_lshl_add_u64 v[218:219], v[240:241], 0, s[0:1]
	s_mov_b32 m0, s76
	s_nop 0
	global_load_lds_dwordx4 v[218:219], off
	s_waitcnt vmcnt(8)
	s_waitcnt lgkmcnt(0)
	s_barrier
	s_nop 0
	s_waitcnt lgkmcnt(0)
	v_mfma_f32_16x16x32_bf16 v[62:65], v[130:133], v[162:165], v[62:65]
	v_mfma_f32_16x16x32_bf16 v[58:61], v[138:141], v[162:165], v[58:61]
	v_mfma_f32_16x16x32_bf16 v[54:57], v[130:133], v[170:173], v[54:57]
	v_mfma_f32_16x16x32_bf16 v[50:53], v[138:141], v[170:173], v[50:53]
	v_mfma_f32_16x16x32_bf16 v[38:41], v[130:133], v[178:181], v[38:41]
	v_mfma_f32_16x16x32_bf16 v[34:37], v[138:141], v[178:181], v[34:37]
	v_mfma_f32_16x16x32_bf16 v[22:25], v[130:133], v[210:213], v[22:25]
	v_mfma_f32_16x16x32_bf16 v[18:21], v[138:141], v[210:213], v[18:21]
	v_mfma_f32_16x16x32_bf16 v[62:65], v[134:137], v[166:169], v[62:65]
	v_mfma_f32_16x16x32_bf16 v[58:61], v[142:145], v[166:169], v[58:61]
	v_mfma_f32_16x16x32_bf16 v[54:57], v[134:137], v[174:177], v[54:57]
	v_mfma_f32_16x16x32_bf16 v[50:53], v[142:145], v[174:177], v[50:53]
	v_mfma_f32_16x16x32_bf16 v[38:41], v[134:137], v[182:185], v[38:41]
	v_mfma_f32_16x16x32_bf16 v[34:37], v[142:145], v[182:185], v[34:37]
	v_mfma_f32_16x16x32_bf16 v[22:25], v[134:137], v[214:217], v[22:25]
	v_mfma_f32_16x16x32_bf16 v[18:21], v[142:145], v[214:217], v[18:21]
	s_nop 0
	s_nop 0
	v_mfma_f32_16x16x32_bf16 v[46:49], v[146:149], v[162:165], v[46:49]
	v_mfma_f32_16x16x32_bf16 v[42:45], v[154:157], v[162:165], v[42:45]
	v_mfma_f32_16x16x32_bf16 v[30:33], v[146:149], v[170:173], v[30:33]
	v_mfma_f32_16x16x32_bf16 v[26:29], v[154:157], v[170:173], v[26:29]
	v_mfma_f32_16x16x32_bf16 v[14:17], v[146:149], v[178:181], v[14:17]
	v_mfma_f32_16x16x32_bf16 v[10:13], v[154:157], v[178:181], v[10:13]
	v_mfma_f32_16x16x32_bf16 v[6:9], v[146:149], v[210:213], v[6:9]
	v_mfma_f32_16x16x32_bf16 v[2:5], v[154:157], v[210:213], v[2:5]
	v_mfma_f32_16x16x32_bf16 v[46:49], v[150:153], v[166:169], v[46:49]
	v_mfma_f32_16x16x32_bf16 v[42:45], v[158:161], v[166:169], v[42:45]
	v_mfma_f32_16x16x32_bf16 v[30:33], v[150:153], v[174:177], v[30:33]
	v_mfma_f32_16x16x32_bf16 v[26:29], v[158:161], v[174:177], v[26:29]
	v_mfma_f32_16x16x32_bf16 v[14:17], v[150:153], v[182:185], v[14:17]
	v_mfma_f32_16x16x32_bf16 v[10:13], v[158:161], v[182:185], v[10:13]
	v_mfma_f32_16x16x32_bf16 v[6:9], v[150:153], v[214:217], v[6:9]
	v_mfma_f32_16x16x32_bf16 v[2:5], v[158:161], v[214:217], v[2:5]
	s_nop 0
	s_barrier
	s_add_u32 s86, s86, 0x100
	s_addc_u32 s87, s87, 0
	s_cmp_ge_i32 s3, s83
	s_mov_b64 s[46:47], s[22:23]
	s_mov_b32 s2, s3
	s_cbranch_scc0 .LBB0_1588
	s_setprio 0
	s_and_b64 vcc, exec, s[54:55]
	s_cbranch_vccz .LBB0_1591
	s_barrier
